# mixer v3: sequence-start runs skip pre-sequence conv rows (edge workgroups no longer the P2 pole), no per-row edge branches; + diet
# speedup vs baseline: 1.0089x; 1.0013x over previous
;     __device__ __forceinline__ bf16_t* U() const { return (bf16_t*)(ws + WS_U); }
;     __device__ __forceinline__ bf16_t* P() const { return (bf16_t*)(ws + WS_P); }
;     __device__ __forceinline__ bf16_t* MIX() const { return (bf16_t*)(ws + WS_MIX); }
; __device__ __forceinline__ void mixer_prompt_run(const Args& p, int run, int c2) {
;     const int b = run >> 7, t0 = (run & 127) * 16;
;     const unsigned* U32 = (const unsigned*)p.U(); const unsigned* P32 = (const unsigned*)p.P(); unsigned* M32 = (unsigned*)p.MIX();
;     const size_t rowb = (size_t)b * SEQ;
;     {
;         unsigned pin[31];
; #pragma unroll
;         for (int i = 0; i < 31; ++i) { const int t = t0 - 15 + i; const unsigned v = P32[(rowb + (t >= 0 ? t : 0)) * 256 + c2]; pin[i] = (t >= 0) ? v : 0u; }
;         const int gi = __builtin_amdgcn_readfirstlane(c2 >> 6);
;         unsigned* dst = M32 + (rowb + t0) * 512 + 256 + c2;
;         if (gi == 0) pool_prompt_w<2>(pin, t0, dst); else if (gi == 1) pool_prompt_w<4>(pin, t0, dst); else if (gi == 2) pool_prompt_w<8>(pin, t0, dst); else pool_prompt_w<16>(pin, t0, dst);
.LBB0_604:
	s_andn2_b64 vcc, exec, s[0:1]
	s_cbranch_vccnz .LBB0_601
	s_add_i32 s62, s20, s41
	v_readfirstlane_b32 s75, v192
	v_lshlrev_b32_e32 v105, 2, v164
	s_lshr_b32 s63, s62, 7
	s_and_b32 s64, s62, 0x7f
	s_lshl_b32 s64, s64, 4
	s_lshl_b32 s63, s63, 11
	s_add_i32 s63, s63, s64
	s_lshr_b32 s75, s75, 6
	s_and_b32 s75, s75, 3
	s_sub_i32 s1, s63, 15
	s_lshl_b32 s65, s1, 10
	s_ashr_i32 s0, s65, 31
	s_add_u32 s68, s58, s65
	s_addc_u32 s69, s59, s0
	s_add_u32 s68, s68, 0x5d81000
	s_addc_u32 s69, s69, 0
	global_load_dword v208, v105, s[68:69] offset:-4096
	global_load_dword v209, v105, s[68:69] offset:-3072
	global_load_dword v210, v105, s[68:69] offset:-2048
	global_load_dword v211, v105, s[68:69] offset:-1024
	global_load_dword v212, v105, s[68:69] offset:0
	global_load_dword v213, v105, s[68:69] offset:1024
	global_load_dword v214, v105, s[68:69] offset:2048
	global_load_dword v215, v105, s[68:69] offset:3072
	s_add_u32 s68, s68, 0x2000
	s_addc_u32 s69, s69, 0
	global_load_dword v216, v105, s[68:69] offset:-4096
	global_load_dword v217, v105, s[68:69] offset:-3072
	global_load_dword v218, v105, s[68:69] offset:-2048
	global_load_dword v219, v105, s[68:69] offset:-1024
	global_load_dword v220, v105, s[68:69] offset:0
	global_load_dword v221, v105, s[68:69] offset:1024
	global_load_dword v222, v105, s[68:69] offset:2048
	global_load_dword v223, v105, s[68:69] offset:3072
	s_add_u32 s68, s68, 0x2000
	s_addc_u32 s69, s69, 0
	global_load_dword v224, v105, s[68:69] offset:-4096
	global_load_dword v225, v105, s[68:69] offset:-3072
	global_load_dword v226, v105, s[68:69] offset:-2048
	global_load_dword v227, v105, s[68:69] offset:-1024
	global_load_dword v228, v105, s[68:69] offset:0
	global_load_dword v229, v105, s[68:69] offset:1024
	global_load_dword v230, v105, s[68:69] offset:2048
	global_load_dword v231, v105, s[68:69] offset:3072
	s_add_u32 s68, s68, 0x2000
	s_addc_u32 s69, s69, 0
	global_load_dword v232, v105, s[68:69] offset:-4096
	global_load_dword v233, v105, s[68:69] offset:-3072
	global_load_dword v234, v105, s[68:69] offset:-2048
	global_load_dword v235, v105, s[68:69] offset:-1024
	global_load_dword v236, v105, s[68:69] offset:0
	global_load_dword v237, v105, s[68:69] offset:1024
	global_load_dword v238, v105, s[68:69] offset:2048
	s_waitcnt vmcnt(31)
	global_load_dwordx2 v[106:107], v[2:3], off
	global_load_dwordx2 v[108:109], v[2:3], off offset:2048
	global_load_dwordx2 v[110:111], v[4:5], off
	global_load_dwordx2 v[112:113], v[6:7], off
	global_load_dwordx2 v[114:115], v[8:9], off
	global_load_dwordx2 v[116:117], v[10:11], off
	global_load_dwordx2 v[118:119], v[12:13], off
	global_load_dwordx2 v[120:121], v[14:15], off
	global_load_dwordx2 v[122:123], v[16:17], off
	global_load_dwordx2 v[124:125], v[18:19], off
	global_load_dwordx2 v[126:127], v[20:21], off
	global_load_dwordx2 v[128:129], v[22:23], off
	global_load_dwordx2 v[130:131], v[24:25], off
	global_load_dwordx2 v[132:133], v[26:27], off
	global_load_dwordx2 v[134:135], v[28:29], off
	global_load_dwordx2 v[136:137], v[30:31], off
	global_load_dwordx2 v[138:139], v[32:33], off
	global_load_dwordx2 v[140:141], v[34:35], off
	global_load_dwordx2 v[142:143], v[36:37], off
	global_load_dwordx2 v[144:145], v[38:39], off
	global_load_dwordx2 v[146:147], v[40:41], off
	global_load_dwordx2 v[148:149], v[42:43], off
	global_load_dwordx2 v[150:151], v[44:45], off
	global_load_dwordx2 v[152:153], v[46:47], off
	global_load_dwordx2 v[154:155], v[48:49], off
	global_load_dwordx2 v[156:157], v[50:51], off
	global_load_dwordx2 v[158:159], v[52:53], off
	global_load_dwordx2 v[160:161], v[54:55], off
	s_sub_i32 s1, s63, 30
	s_lshl_b32 s65, s1, 10
	s_ashr_i32 s0, s65, 31
	s_add_u32 s66, s58, s65
	s_addc_u32 s67, s59, s0
	s_add_u32 s66, s66, 0x4d01000
	s_addc_u32 s67, s67, 0
	s_lshl_b32 s65, s63, 11
	s_ashr_i32 s0, s65, 31
	s_add_u32 s70, s58, s65
	s_addc_u32 s71, s59, s0
	s_add_u32 s70, s70, 0x6e01000
	s_addc_u32 s71, s71, 0
	s_mov_b32 s76, s70
	s_mov_b32 s77, s71
	s_lshl_b32 s74, 2, s75
	s_sub_i32 s72, 126, s75
	s_lshl_b32 s72, s72, 23
	s_mov_b32 s73, s72
	v_xor_b32_e32 v239, 16, v165
	v_lshlrev_b32_e32 v239, 2, v239
	s_waitcnt vmcnt(28)
	s_cmp_eq_u32 s64, 0
	s_cbranch_scc0 .Lmx_pnz
	v_mov_b32_e32 v208, 0
	v_mov_b32_e32 v209, 0
	v_mov_b32_e32 v210, 0
	v_mov_b32_e32 v211, 0
	v_mov_b32_e32 v212, 0
	v_mov_b32_e32 v213, 0
	v_mov_b32_e32 v214, 0
	v_mov_b32_e32 v215, 0
	v_mov_b32_e32 v216, 0
	v_mov_b32_e32 v217, 0
	v_mov_b32_e32 v218, 0
	v_mov_b32_e32 v219, 0
	v_mov_b32_e32 v220, 0
	v_mov_b32_e32 v221, 0
	v_mov_b32_e32 v222, 0

; __device__ __forceinline__ f32x2v bf2(unsigned v) { return (f32x2v){bflo(v), bfhi(v)}; }
; __device__ __forceinline__ void mixer_prompt_run(const Args& p, int run, int c2) {
;     ...
; #pragma unroll
;         for (int j = 0; j < 31; ++j) w[j] = *(const f32x2v*)(p.conv_w() + j * 512 + 2 * c2);
;         const f32x2v cb = *(const f32x2v*)(p.conv_b() + 2 * c2);
;         const f32x2v gg = *(const f32x2v*)(p.gn_g() + 2 * c2), gb = *(const f32x2v*)(p.gn_b() + 2 * c2);
; #pragma unroll 1
;         for (int hh = 0; hh < 2; ++hh) {
;             f32x2v a[8];
; #pragma unroll
;             for (int t = 0; t < 8; ++t) a[t] = cb;
; #pragma unroll
;             for (int i = 0; i < 38; ++i) {
;                 const int ti = t0 + 8 * hh - 30 + i; unsigned v = U32[(rowb + (ti >= 0 ? ti : 0)) * 256 + c2]; v = (ti >= 0) ? v : 0u; const f32x2v x = bf2(v);
; #pragma unroll
;                 for (int t = 0; t < 8; ++t) { const int j = i - t; if (j >= 0 && j <= 30) a[t] = w[j] * x + a[t]; }
;                 if (i == 18) asm volatile("" ::: "memory");
;             }
.Lmx_pool_done:
	s_mov_b32 s78, 0xbc800000
	s_mov_b32 s79, 0xbc800000
	s_mov_b32 s80, 0xbfb8aa3b
	s_mov_b32 s81, 0xbfb8aa3b
	s_mov_b32 s86, 0x3f800000
	s_mov_b32 s87, 0x3f800000
	v_mov_b32_e32 v241, 0x3727c5ac
	s_waitcnt vmcnt(30)
	global_load_dword v208, v105, s[66:67] offset:3072
	s_add_u32 s66, s66, 0x2000
	s_addc_u32 s67, s67, 0
	global_load_dword v209, v105, s[66:67] offset:-4096
	global_load_dword v210, v105, s[66:67] offset:-3072
	global_load_dword v211, v105, s[66:67] offset:-2048
	global_load_dword v212, v105, s[66:67] offset:-1024
	global_load_dword v213, v105, s[66:67] offset:0
	global_load_dword v214, v105, s[66:67] offset:1024
	global_load_dword v215, v105, s[66:67] offset:2048
	global_load_dword v216, v105, s[66:67] offset:3072
	s_add_u32 s66, s66, 0x2000
	s_addc_u32 s67, s67, 0
	global_load_dword v217, v105, s[66:67] offset:-4096
	global_load_dword v218, v105, s[66:67] offset:-3072
	global_load_dword v219, v105, s[66:67] offset:-2048
	global_load_dword v220, v105, s[66:67] offset:-1024
	global_load_dword v221, v105, s[66:67] offset:0
	global_load_dword v222, v105, s[66:67] offset:1024
	global_load_dword v223, v105, s[66:67] offset:2048
	global_load_dword v224, v105, s[66:67] offset:3072
	s_add_u32 s66, s66, 0x2000
	s_addc_u32 s67, s67, 0
	global_load_dword v225, v105, s[66:67] offset:-4096
	global_load_dword v226, v105, s[66:67] offset:-3072
	global_load_dword v227, v105, s[66:67] offset:-2048
	global_load_dword v228, v105, s[66:67] offset:-1024
	global_load_dword v229, v105, s[66:67] offset:0
	global_load_dword v230, v105, s[66:67] offset:1024
	global_load_dword v231, v105, s[66:67] offset:2048
	global_load_dword v232, v105, s[66:67] offset:3072
	s_add_u32 s66, s66, 0x2000
	s_addc_u32 s67, s67, 0
	global_load_dword v233, v105, s[66:67] offset:-4096
	global_load_dword v234, v105, s[66:67] offset:-3072
	global_load_dword v235, v105, s[66:67] offset:-2048
	global_load_dword v236, v105, s[66:67] offset:-1024
	global_load_dword v237, v105, s[66:67] offset:0
	global_load_dword v238, v105, s[66:67] offset:1024
	s_waitcnt vmcnt(47)
	s_cmp_lt_i32 s64, 32
	s_cbranch_scc1 .Lmx_edge
	v_lshlrev_b32_e32 v96, 16, v193
	v_and_b32_e32 v97, 0xffff0000, v193
	v_pk_fma_f32 v[172:173], v[106:107], v[96:97], v[90:91]
	v_lshlrev_b32_e32 v98, 16, v194
	v_and_b32_e32 v99, 0xffff0000, v194
	v_pk_fma_f32 v[172:173], v[108:109], v[98:99], v[172:173]
	v_pk_fma_f32 v[174:175], v[106:107], v[98:99], v[90:91]
	v_lshlrev_b32_e32 v96, 16, v195
	v_and_b32_e32 v97, 0xffff0000, v195
	v_pk_fma_f32 v[172:173], v[110:111], v[96:97], v[172:173]
	v_pk_fma_f32 v[174:175], v[108:109], v[96:97], v[174:175]
	v_pk_fma_f32 v[176:177], v[106:107], v[96:97], v[90:91]
	v_lshlrev_b32_e32 v98, 16, v196
	v_and_b32_e32 v99, 0xffff0000, v196
	v_pk_fma_f32 v[172:173], v[112:113], v[98:99], v[172:173]
	v_pk_fma_f32 v[174:175], v[110:111], v[98:99], v[174:175]
	v_pk_fma_f32 v[176:177], v[108:109], v[98:99], v[176:177]
	v_pk_fma_f32 v[178:179], v[106:107], v[98:99], v[90:91]
	v_lshlrev_b32_e32 v96, 16, v197
	v_and_b32_e32 v97, 0xffff0000, v197
	v_pk_fma_f32 v[172:173], v[114:115], v[96:97], v[172:173]
	v_pk_fma_f32 v[174:175], v[112:113], v[96:97], v[174:175]
	v_pk_fma_f32 v[176:177], v[110:111], v[96:97], v[176:177]
	v_pk_fma_f32 v[178:179], v[108:109], v[96:97], v[178:179]
	v_pk_fma_f32 v[180:181], v[106:107], v[96:97], v[90:91]
	v_lshlrev_b32_e32 v98, 16, v198
	v_and_b32_e32 v99, 0xffff0000, v198
	v_pk_fma_f32 v[172:173], v[116:117], v[98:99], v[172:173]
	v_pk_fma_f32 v[174:175], v[114:115], v[98:99], v[174:175]
	v_pk_fma_f32 v[176:177], v[112:113], v[98:99], v[176:177]
	v_pk_fma_f32 v[178:179], v[110:111], v[98:99], v[178:179]
	v_pk_fma_f32 v[180:181], v[108:109], v[98:99], v[180:181]
	v_pk_fma_f32 v[182:183], v[106:107], v[98:99], v[90:91]
	v_lshlrev_b32_e32 v96, 16, v199
	v_and_b32_e32 v97, 0xffff0000, v199
	v_pk_fma_f32 v[172:173], v[118:119], v[96:97], v[172:173]
	v_pk_fma_f32 v[174:175], v[116:117], v[96:97], v[174:175]
	v_pk_fma_f32 v[176:177], v[114:115], v[96:97], v[176:177]
	v_pk_fma_f32 v[178:179], v[112:113], v[96:97], v[178:179]
	v_pk_fma_f32 v[180:181], v[110:111], v[96:97], v[180:181]
	v_pk_fma_f32 v[182:183], v[108:109], v[96:97], v[182:183]
	v_pk_fma_f32 v[184:185], v[106:107], v[96:97], v[90:91]
	v_lshlrev_b32_e32 v98, 16, v200
	v_and_b32_e32 v99, 0xffff0000, v200
	v_pk_fma_f32 v[172:173], v[120:121], v[98:99], v[172:173]
	v_pk_fma_f32 v[174:175], v[118:119], v[98:99], v[174:175]
	v_pk_fma_f32 v[176:177], v[116:117], v[98:99], v[176:177]
	v_pk_fma_f32 v[178:179], v[114:115], v[98:99], v[178:179]
	v_pk_fma_f32 v[180:181], v[112:113], v[98:99], v[180:181]
	v_pk_fma_f32 v[182:183], v[110:111], v[98:99], v[182:183]
	v_pk_fma_f32 v[184:185], v[108:109], v[98:99], v[184:185]
	v_pk_fma_f32 v[186:187], v[106:107], v[98:99], v[90:91]
	v_lshlrev_b32_e32 v96, 16, v201
	v_and_b32_e32 v97, 0xffff0000, v201
	v_pk_fma_f32 v[172:173], v[122:123], v[96:97], v[172:173]
	v_pk_fma_f32 v[174:175], v[120:121], v[96:97], v[174:175]
	v_pk_fma_f32 v[176:177], v[118:119], v[96:97], v[176:177]
	v_pk_fma_f32 v[178:179], v[116:117], v[96:97], v[178:179]
	v_pk_fma_f32 v[180:181], v[114:115], v[96:97], v[180:181]
	v_pk_fma_f32 v[182:183], v[112:113], v[96:97], v[182:183]
	v_pk_fma_f32 v[184:185], v[110:111], v[96:97], v[184:185]
	v_pk_fma_f32 v[186:187], v[108:109], v[96:97], v[186:187]
	v_pk_fma_f32 v[188:189], v[106:107], v[96:97], v[90:91]
	v_lshlrev_b32_e32 v98, 16, v202
	v_and_b32_e32 v99, 0xffff0000, v202
	v_pk_fma_f32 v[172:173], v[124:125], v[98:99], v[172:173]
	v_pk_fma_f32 v[174:175], v[122:123], v[98:99], v[174:175]
	v_pk_fma_f32 v[176:177], v[120:121], v[98:99], v[176:177]
; __device__ __forceinline__ f32x2v bf2(unsigned v) { return (f32x2v){bflo(v), bfhi(v)}; }
; __device__ __forceinline__ void mixer_prompt_run(const Args& p, int run, int c2) {
;     ...
;             for (int i = 0; i < 38; ++i) {
;                 const int ti = t0 + 8 * hh - 30 + i; unsigned v = U32[(rowb + (ti >= 0 ? ti : 0)) * 256 + c2]; v = (ti >= 0) ? v : 0u; const f32x2v x = bf2(v);
; #pragma unroll
;                 for (int t = 0; t < 8; ++t) { const int j = i - t; if (j >= 0 && j <= 30) a[t] = w[j] * x + a[t]; }
;                 if (i == 18) asm volatile("" ::: "memory");
;             }
	v_pk_fma_f32 v[178:179], v[118:119], v[98:99], v[178:179]
	v_pk_fma_f32 v[180:181], v[116:117], v[98:99], v[180:181]
	v_pk_fma_f32 v[182:183], v[114:115], v[98:99], v[182:183]
	v_pk_fma_f32 v[184:185], v[112:113], v[98:99], v[184:185]
	v_pk_fma_f32 v[186:187], v[110:111], v[98:99], v[186:187]
	v_pk_fma_f32 v[188:189], v[108:109], v[98:99], v[188:189]
	v_pk_fma_f32 v[190:191], v[106:107], v[98:99], v[90:91]
	v_lshlrev_b32_e32 v96, 16, v203
	v_and_b32_e32 v97, 0xffff0000, v203
	v_pk_fma_f32 v[172:173], v[126:127], v[96:97], v[172:173]
	v_pk_fma_f32 v[174:175], v[124:125], v[96:97], v[174:175]
	v_pk_fma_f32 v[176:177], v[122:123], v[96:97], v[176:177]
	v_pk_fma_f32 v[178:179], v[120:121], v[96:97], v[178:179]
	v_pk_fma_f32 v[180:181], v[118:119], v[96:97], v[180:181]
	v_pk_fma_f32 v[182:183], v[116:117], v[96:97], v[182:183]
	v_pk_fma_f32 v[184:185], v[114:115], v[96:97], v[184:185]
	v_pk_fma_f32 v[186:187], v[112:113], v[96:97], v[186:187]
	v_pk_fma_f32 v[188:189], v[110:111], v[96:97], v[188:189]
	v_pk_fma_f32 v[190:191], v[108:109], v[96:97], v[190:191]
	v_pk_fma_f32 v[78:79], v[106:107], v[96:97], v[90:91]
	v_lshlrev_b32_e32 v98, 16, v204
	v_and_b32_e32 v99, 0xffff0000, v204
	v_pk_fma_f32 v[172:173], v[128:129], v[98:99], v[172:173]
	v_pk_fma_f32 v[174:175], v[126:127], v[98:99], v[174:175]
	v_pk_fma_f32 v[176:177], v[124:125], v[98:99], v[176:177]
	v_pk_fma_f32 v[178:179], v[122:123], v[98:99], v[178:179]
	v_pk_fma_f32 v[180:181], v[120:121], v[98:99], v[180:181]
	v_pk_fma_f32 v[182:183], v[118:119], v[98:99], v[182:183]
	v_pk_fma_f32 v[184:185], v[116:117], v[98:99], v[184:185]
	v_pk_fma_f32 v[186:187], v[114:115], v[98:99], v[186:187]
	v_pk_fma_f32 v[188:189], v[112:113], v[98:99], v[188:189]
	v_pk_fma_f32 v[190:191], v[110:111], v[98:99], v[190:191]
	v_pk_fma_f32 v[78:79], v[108:109], v[98:99], v[78:79]
	v_pk_fma_f32 v[80:81], v[106:107], v[98:99], v[90:91]
	v_lshlrev_b32_e32 v96, 16, v205
	v_and_b32_e32 v97, 0xffff0000, v205
	v_pk_fma_f32 v[172:173], v[130:131], v[96:97], v[172:173]
	v_pk_fma_f32 v[174:175], v[128:129], v[96:97], v[174:175]
	v_pk_fma_f32 v[176:177], v[126:127], v[96:97], v[176:177]
	v_pk_fma_f32 v[178:179], v[124:125], v[96:97], v[178:179]
	v_pk_fma_f32 v[180:181], v[122:123], v[96:97], v[180:181]
	v_pk_fma_f32 v[182:183], v[120:121], v[96:97], v[182:183]
	v_pk_fma_f32 v[184:185], v[118:119], v[96:97], v[184:185]
	v_pk_fma_f32 v[186:187], v[116:117], v[96:97], v[186:187]
	v_pk_fma_f32 v[188:189], v[114:115], v[96:97], v[188:189]
	v_pk_fma_f32 v[190:191], v[112:113], v[96:97], v[190:191]
	v_pk_fma_f32 v[78:79], v[110:111], v[96:97], v[78:79]
	v_pk_fma_f32 v[80:81], v[108:109], v[96:97], v[80:81]
	v_pk_fma_f32 v[82:83], v[106:107], v[96:97], v[90:91]
	v_lshlrev_b32_e32 v98, 16, v206
	v_and_b32_e32 v99, 0xffff0000, v206
	v_pk_fma_f32 v[172:173], v[132:133], v[98:99], v[172:173]
	v_pk_fma_f32 v[174:175], v[130:131], v[98:99], v[174:175]
	v_pk_fma_f32 v[176:177], v[128:129], v[98:99], v[176:177]
	v_pk_fma_f32 v[178:179], v[126:127], v[98:99], v[178:179]
	v_pk_fma_f32 v[180:181], v[124:125], v[98:99], v[180:181]
	v_pk_fma_f32 v[182:183], v[122:123], v[98:99], v[182:183]
	v_pk_fma_f32 v[184:185], v[120:121], v[98:99], v[184:185]
	v_pk_fma_f32 v[186:187], v[118:119], v[98:99], v[186:187]
	v_pk_fma_f32 v[188:189], v[116:117], v[98:99], v[188:189]
	v_pk_fma_f32 v[190:191], v[114:115], v[98:99], v[190:191]
	v_pk_fma_f32 v[78:79], v[112:113], v[98:99], v[78:79]
	v_pk_fma_f32 v[80:81], v[110:111], v[98:99], v[80:81]
	v_pk_fma_f32 v[82:83], v[108:109], v[98:99], v[82:83]
	v_pk_fma_f32 v[84:85], v[106:107], v[98:99], v[90:91]
.Lmx_row14:
	v_lshlrev_b32_e32 v96, 16, v207
	v_and_b32_e32 v97, 0xffff0000, v207
	v_pk_fma_f32 v[172:173], v[134:135], v[96:97], v[172:173]
	v_pk_fma_f32 v[174:175], v[132:133], v[96:97], v[174:175]
	v_pk_fma_f32 v[176:177], v[130:131], v[96:97], v[176:177]
	v_pk_fma_f32 v[178:179], v[128:129], v[96:97], v[178:179]
	v_pk_fma_f32 v[180:181], v[126:127], v[96:97], v[180:181]
	v_pk_fma_f32 v[182:183], v[124:125], v[96:97], v[182:183]
	v_pk_fma_f32 v[184:185], v[122:123], v[96:97], v[184:185]
	v_pk_fma_f32 v[186:187], v[120:121], v[96:97], v[186:187]
	v_pk_fma_f32 v[188:189], v[118:119], v[96:97], v[188:189]
	v_pk_fma_f32 v[190:191], v[116:117], v[96:97], v[190:191]
	v_pk_fma_f32 v[78:79], v[114:115], v[96:97], v[78:79]
	v_pk_fma_f32 v[80:81], v[112:113], v[96:97], v[80:81]
	v_pk_fma_f32 v[82:83], v[110:111], v[96:97], v[82:83]
	v_pk_fma_f32 v[84:85], v[108:109], v[96:97], v[84:85]
	v_pk_fma_f32 v[86:87], v[106:107], v[96:97], v[90:91]
	s_waitcnt vmcnt(30)
	v_lshlrev_b32_e32 v98, 16, v208
	v_and_b32_e32 v99, 0xffff0000, v208
	v_pk_fma_f32 v[172:173], v[136:137], v[98:99], v[172:173]
	v_pk_fma_f32 v[174:175], v[134:135], v[98:99], v[174:175]
	v_pk_fma_f32 v[176:177], v[132:133], v[98:99], v[176:177]
	v_pk_fma_f32 v[178:179], v[130:131], v[98:99], v[178:179]
	v_pk_fma_f32 v[180:181], v[128:129], v[98:99], v[180:181]
	v_pk_fma_f32 v[182:183], v[126:127], v[98:99], v[182:183]
	v_pk_fma_f32 v[184:185], v[124:125], v[98:99], v[184:185]
	v_pk_fma_f32 v[186:187], v[122:123], v[98:99], v[186:187]
	v_pk_fma_f32 v[188:189], v[120:121], v[98:99], v[188:189]
	v_pk_fma_f32 v[190:191], v[118:119], v[98:99], v[190:191]
	v_pk_fma_f32 v[78:79], v[116:117], v[98:99], v[78:79]
	v_pk_fma_f32 v[80:81], v[114:115], v[98:99], v[80:81]
	v_pk_fma_f32 v[82:83], v[112:113], v[98:99], v[82:83]
	v_pk_fma_f32 v[84:85], v[110:111], v[98:99], v[84:85]
	v_pk_fma_f32 v[86:87], v[108:109], v[98:99], v[86:87]
	v_pk_fma_f32 v[88:89], v[106:107], v[98:99], v[90:91]
	s_waitcnt vmcnt(29)
; __device__ __forceinline__ f32x2v bf2(unsigned v) { return (f32x2v){bflo(v), bfhi(v)}; }
; __device__ __forceinline__ void mixer_prompt_run(const Args& p, int run, int c2) {
;     ...
;             for (int i = 0; i < 38; ++i) {
;                 const int ti = t0 + 8 * hh - 30 + i; unsigned v = U32[(rowb + (ti >= 0 ? ti : 0)) * 256 + c2]; v = (ti >= 0) ? v : 0u; const f32x2v x = bf2(v);
; #pragma unroll
;                 for (int t = 0; t < 8; ++t) { const int j = i - t; if (j >= 0 && j <= 30) a[t] = w[j] * x + a[t]; }
;                 if (i == 18) asm volatile("" ::: "memory");
;             }
	v_lshlrev_b32_e32 v96, 16, v209
	v_and_b32_e32 v97, 0xffff0000, v209
	v_pk_fma_f32 v[172:173], v[138:139], v[96:97], v[172:173]
	v_pk_fma_f32 v[174:175], v[136:137], v[96:97], v[174:175]
	v_pk_fma_f32 v[176:177], v[134:135], v[96:97], v[176:177]
	v_pk_fma_f32 v[178:179], v[132:133], v[96:97], v[178:179]
	v_pk_fma_f32 v[180:181], v[130:131], v[96:97], v[180:181]
	v_pk_fma_f32 v[182:183], v[128:129], v[96:97], v[182:183]
	v_pk_fma_f32 v[184:185], v[126:127], v[96:97], v[184:185]
	v_pk_fma_f32 v[186:187], v[124:125], v[96:97], v[186:187]
	v_pk_fma_f32 v[188:189], v[122:123], v[96:97], v[188:189]
	v_pk_fma_f32 v[190:191], v[120:121], v[96:97], v[190:191]
	v_pk_fma_f32 v[78:79], v[118:119], v[96:97], v[78:79]
	v_pk_fma_f32 v[80:81], v[116:117], v[96:97], v[80:81]
	v_pk_fma_f32 v[82:83], v[114:115], v[96:97], v[82:83]
	v_pk_fma_f32 v[84:85], v[112:113], v[96:97], v[84:85]
	v_pk_fma_f32 v[86:87], v[110:111], v[96:97], v[86:87]
	v_pk_fma_f32 v[88:89], v[108:109], v[96:97], v[88:89]
	s_waitcnt vmcnt(28)
	v_lshlrev_b32_e32 v98, 16, v210
	v_and_b32_e32 v99, 0xffff0000, v210
	v_pk_fma_f32 v[172:173], v[140:141], v[98:99], v[172:173]
	v_pk_fma_f32 v[174:175], v[138:139], v[98:99], v[174:175]
	v_pk_fma_f32 v[176:177], v[136:137], v[98:99], v[176:177]
	v_pk_fma_f32 v[178:179], v[134:135], v[98:99], v[178:179]
	v_pk_fma_f32 v[180:181], v[132:133], v[98:99], v[180:181]
	v_pk_fma_f32 v[182:183], v[130:131], v[98:99], v[182:183]
	v_pk_fma_f32 v[184:185], v[128:129], v[98:99], v[184:185]
	v_pk_fma_f32 v[186:187], v[126:127], v[98:99], v[186:187]
	v_pk_fma_f32 v[188:189], v[124:125], v[98:99], v[188:189]
	v_pk_fma_f32 v[190:191], v[122:123], v[98:99], v[190:191]
	v_pk_fma_f32 v[78:79], v[120:121], v[98:99], v[78:79]
	v_pk_fma_f32 v[80:81], v[118:119], v[98:99], v[80:81]
	v_pk_fma_f32 v[82:83], v[116:117], v[98:99], v[82:83]
	v_pk_fma_f32 v[84:85], v[114:115], v[98:99], v[84:85]
	v_pk_fma_f32 v[86:87], v[112:113], v[98:99], v[86:87]
	v_pk_fma_f32 v[88:89], v[110:111], v[98:99], v[88:89]
	s_waitcnt vmcnt(27)
	v_lshlrev_b32_e32 v96, 16, v211
	v_and_b32_e32 v97, 0xffff0000, v211
	v_pk_fma_f32 v[172:173], v[142:143], v[96:97], v[172:173]
	v_pk_fma_f32 v[174:175], v[140:141], v[96:97], v[174:175]
	v_pk_fma_f32 v[176:177], v[138:139], v[96:97], v[176:177]
	v_pk_fma_f32 v[178:179], v[136:137], v[96:97], v[178:179]
	v_pk_fma_f32 v[180:181], v[134:135], v[96:97], v[180:181]
	v_pk_fma_f32 v[182:183], v[132:133], v[96:97], v[182:183]
	v_pk_fma_f32 v[184:185], v[130:131], v[96:97], v[184:185]
	v_pk_fma_f32 v[186:187], v[128:129], v[96:97], v[186:187]
	v_pk_fma_f32 v[188:189], v[126:127], v[96:97], v[188:189]
	v_pk_fma_f32 v[190:191], v[124:125], v[96:97], v[190:191]
	v_pk_fma_f32 v[78:79], v[122:123], v[96:97], v[78:79]
	v_pk_fma_f32 v[80:81], v[120:121], v[96:97], v[80:81]
	v_pk_fma_f32 v[82:83], v[118:119], v[96:97], v[82:83]
	v_pk_fma_f32 v[84:85], v[116:117], v[96:97], v[84:85]
	v_pk_fma_f32 v[86:87], v[114:115], v[96:97], v[86:87]
	v_pk_fma_f32 v[88:89], v[112:113], v[96:97], v[88:89]
	s_waitcnt vmcnt(26)
	v_lshlrev_b32_e32 v98, 16, v212
	v_and_b32_e32 v99, 0xffff0000, v212
	v_pk_fma_f32 v[172:173], v[144:145], v[98:99], v[172:173]
	v_pk_fma_f32 v[174:175], v[142:143], v[98:99], v[174:175]
	v_pk_fma_f32 v[176:177], v[140:141], v[98:99], v[176:177]
	v_pk_fma_f32 v[178:179], v[138:139], v[98:99], v[178:179]
	v_pk_fma_f32 v[180:181], v[136:137], v[98:99], v[180:181]
	v_pk_fma_f32 v[182:183], v[134:135], v[98:99], v[182:183]
	v_pk_fma_f32 v[184:185], v[132:133], v[98:99], v[184:185]
	v_pk_fma_f32 v[186:187], v[130:131], v[98:99], v[186:187]
	v_pk_fma_f32 v[188:189], v[128:129], v[98:99], v[188:189]
	v_pk_fma_f32 v[190:191], v[126:127], v[98:99], v[190:191]
	v_pk_fma_f32 v[78:79], v[124:125], v[98:99], v[78:79]
	v_pk_fma_f32 v[80:81], v[122:123], v[98:99], v[80:81]
	v_pk_fma_f32 v[82:83], v[120:121], v[98:99], v[82:83]
	v_pk_fma_f32 v[84:85], v[118:119], v[98:99], v[84:85]
	v_pk_fma_f32 v[86:87], v[116:117], v[98:99], v[86:87]
	v_pk_fma_f32 v[88:89], v[114:115], v[98:99], v[88:89]
	s_waitcnt vmcnt(25)
	v_lshlrev_b32_e32 v96, 16, v213
	v_and_b32_e32 v97, 0xffff0000, v213
	v_pk_fma_f32 v[172:173], v[146:147], v[96:97], v[172:173]
	v_pk_fma_f32 v[174:175], v[144:145], v[96:97], v[174:175]
	v_pk_fma_f32 v[176:177], v[142:143], v[96:97], v[176:177]
	v_pk_fma_f32 v[178:179], v[140:141], v[96:97], v[178:179]
	v_pk_fma_f32 v[180:181], v[138:139], v[96:97], v[180:181]
	v_pk_fma_f32 v[182:183], v[136:137], v[96:97], v[182:183]
	v_pk_fma_f32 v[184:185], v[134:135], v[96:97], v[184:185]
	v_pk_fma_f32 v[186:187], v[132:133], v[96:97], v[186:187]
	v_pk_fma_f32 v[188:189], v[130:131], v[96:97], v[188:189]
	v_pk_fma_f32 v[190:191], v[128:129], v[96:97], v[190:191]
	v_pk_fma_f32 v[78:79], v[126:127], v[96:97], v[78:79]
	v_pk_fma_f32 v[80:81], v[124:125], v[96:97], v[80:81]
	v_pk_fma_f32 v[82:83], v[122:123], v[96:97], v[82:83]
	v_pk_fma_f32 v[84:85], v[120:121], v[96:97], v[84:85]
	v_pk_fma_f32 v[86:87], v[118:119], v[96:97], v[86:87]
	v_pk_fma_f32 v[88:89], v[116:117], v[96:97], v[88:89]
	s_waitcnt vmcnt(24)
	v_lshlrev_b32_e32 v98, 16, v214
	v_and_b32_e32 v99, 0xffff0000, v214
	v_pk_fma_f32 v[172:173], v[148:149], v[98:99], v[172:173]
	v_pk_fma_f32 v[174:175], v[146:147], v[98:99], v[174:175]
	v_pk_fma_f32 v[176:177], v[144:145], v[98:99], v[176:177]
	v_pk_fma_f32 v[178:179], v[142:143], v[98:99], v[178:179]
	v_pk_fma_f32 v[180:181], v[140:141], v[98:99], v[180:181]
	v_pk_fma_f32 v[182:183], v[138:139], v[98:99], v[182:183]
	v_pk_fma_f32 v[184:185], v[136:137], v[98:99], v[184:185]
	v_pk_fma_f32 v[186:187], v[134:135], v[98:99], v[186:187]
	v_pk_fma_f32 v[188:189], v[132:133], v[98:99], v[188:189]
	v_pk_fma_f32 v[190:191], v[130:131], v[98:99], v[190:191]
	v_pk_fma_f32 v[78:79], v[128:129], v[98:99], v[78:79]
	v_pk_fma_f32 v[80:81], v[126:127], v[98:99], v[80:81]
	v_pk_fma_f32 v[82:83], v[124:125], v[98:99], v[82:83]
	v_pk_fma_f32 v[84:85], v[122:123], v[98:99], v[84:85]
	v_pk_fma_f32 v[86:87], v[120:121], v[98:99], v[86:87]
	v_pk_fma_f32 v[88:89], v[118:119], v[98:99], v[88:89]
	s_waitcnt vmcnt(23)
; __device__ __forceinline__ f32x2v bf2(unsigned v) { return (f32x2v){bflo(v), bfhi(v)}; }
; __device__ __forceinline__ void mixer_prompt_run(const Args& p, int run, int c2) {
;     ...
;             for (int i = 0; i < 38; ++i) {
;                 const int ti = t0 + 8 * hh - 30 + i; unsigned v = U32[(rowb + (ti >= 0 ? ti : 0)) * 256 + c2]; v = (ti >= 0) ? v : 0u; const f32x2v x = bf2(v);
; #pragma unroll
;                 for (int t = 0; t < 8; ++t) { const int j = i - t; if (j >= 0 && j <= 30) a[t] = w[j] * x + a[t]; }
;                 if (i == 18) asm volatile("" ::: "memory");
;             }
	v_lshlrev_b32_e32 v96, 16, v215
	v_and_b32_e32 v97, 0xffff0000, v215
	v_pk_fma_f32 v[172:173], v[150:151], v[96:97], v[172:173]
	v_pk_fma_f32 v[174:175], v[148:149], v[96:97], v[174:175]
	v_pk_fma_f32 v[176:177], v[146:147], v[96:97], v[176:177]
	v_pk_fma_f32 v[178:179], v[144:145], v[96:97], v[178:179]
	v_pk_fma_f32 v[180:181], v[142:143], v[96:97], v[180:181]
	v_pk_fma_f32 v[182:183], v[140:141], v[96:97], v[182:183]
	v_pk_fma_f32 v[184:185], v[138:139], v[96:97], v[184:185]
	v_pk_fma_f32 v[186:187], v[136:137], v[96:97], v[186:187]
	v_pk_fma_f32 v[188:189], v[134:135], v[96:97], v[188:189]
	v_pk_fma_f32 v[190:191], v[132:133], v[96:97], v[190:191]
	v_pk_fma_f32 v[78:79], v[130:131], v[96:97], v[78:79]
	v_pk_fma_f32 v[80:81], v[128:129], v[96:97], v[80:81]
	v_pk_fma_f32 v[82:83], v[126:127], v[96:97], v[82:83]
	v_pk_fma_f32 v[84:85], v[124:125], v[96:97], v[84:85]
	v_pk_fma_f32 v[86:87], v[122:123], v[96:97], v[86:87]
	v_pk_fma_f32 v[88:89], v[120:121], v[96:97], v[88:89]
	s_waitcnt vmcnt(22)
	v_lshlrev_b32_e32 v98, 16, v216
	v_and_b32_e32 v99, 0xffff0000, v216
	v_pk_fma_f32 v[172:173], v[152:153], v[98:99], v[172:173]
	v_pk_fma_f32 v[174:175], v[150:151], v[98:99], v[174:175]
	v_pk_fma_f32 v[176:177], v[148:149], v[98:99], v[176:177]
	v_pk_fma_f32 v[178:179], v[146:147], v[98:99], v[178:179]
	v_pk_fma_f32 v[180:181], v[144:145], v[98:99], v[180:181]
	v_pk_fma_f32 v[182:183], v[142:143], v[98:99], v[182:183]
	v_pk_fma_f32 v[184:185], v[140:141], v[98:99], v[184:185]
	v_pk_fma_f32 v[186:187], v[138:139], v[98:99], v[186:187]
	v_pk_fma_f32 v[188:189], v[136:137], v[98:99], v[188:189]
	v_pk_fma_f32 v[190:191], v[134:135], v[98:99], v[190:191]
	v_pk_fma_f32 v[78:79], v[132:133], v[98:99], v[78:79]
	v_pk_fma_f32 v[80:81], v[130:131], v[98:99], v[80:81]
	v_pk_fma_f32 v[82:83], v[128:129], v[98:99], v[82:83]
	v_pk_fma_f32 v[84:85], v[126:127], v[98:99], v[84:85]
	v_pk_fma_f32 v[86:87], v[124:125], v[98:99], v[86:87]
	v_pk_fma_f32 v[88:89], v[122:123], v[98:99], v[88:89]
	s_waitcnt vmcnt(21)
	v_lshlrev_b32_e32 v96, 16, v217
	v_and_b32_e32 v97, 0xffff0000, v217
	v_pk_fma_f32 v[172:173], v[154:155], v[96:97], v[172:173]
	v_pk_fma_f32 v[174:175], v[152:153], v[96:97], v[174:175]
	v_pk_fma_f32 v[176:177], v[150:151], v[96:97], v[176:177]
	v_pk_fma_f32 v[178:179], v[148:149], v[96:97], v[178:179]
	v_pk_fma_f32 v[180:181], v[146:147], v[96:97], v[180:181]
	v_pk_fma_f32 v[182:183], v[144:145], v[96:97], v[182:183]
	v_pk_fma_f32 v[184:185], v[142:143], v[96:97], v[184:185]
	v_pk_fma_f32 v[186:187], v[140:141], v[96:97], v[186:187]
	v_pk_fma_f32 v[188:189], v[138:139], v[96:97], v[188:189]
	v_pk_fma_f32 v[190:191], v[136:137], v[96:97], v[190:191]
	v_pk_fma_f32 v[78:79], v[134:135], v[96:97], v[78:79]
	v_pk_fma_f32 v[80:81], v[132:133], v[96:97], v[80:81]
	v_pk_fma_f32 v[82:83], v[130:131], v[96:97], v[82:83]
	v_pk_fma_f32 v[84:85], v[128:129], v[96:97], v[84:85]
	v_pk_fma_f32 v[86:87], v[126:127], v[96:97], v[86:87]
	v_pk_fma_f32 v[88:89], v[124:125], v[96:97], v[88:89]
	s_waitcnt vmcnt(20)
	v_lshlrev_b32_e32 v98, 16, v218
	v_and_b32_e32 v99, 0xffff0000, v218
	v_pk_fma_f32 v[172:173], v[156:157], v[98:99], v[172:173]
	v_pk_fma_f32 v[174:175], v[154:155], v[98:99], v[174:175]
	v_pk_fma_f32 v[176:177], v[152:153], v[98:99], v[176:177]
	v_pk_fma_f32 v[178:179], v[150:151], v[98:99], v[178:179]
	v_pk_fma_f32 v[180:181], v[148:149], v[98:99], v[180:181]
	v_pk_fma_f32 v[182:183], v[146:147], v[98:99], v[182:183]
	v_pk_fma_f32 v[184:185], v[144:145], v[98:99], v[184:185]
	v_pk_fma_f32 v[186:187], v[142:143], v[98:99], v[186:187]
	v_pk_fma_f32 v[188:189], v[140:141], v[98:99], v[188:189]
	v_pk_fma_f32 v[190:191], v[138:139], v[98:99], v[190:191]
	v_pk_fma_f32 v[78:79], v[136:137], v[98:99], v[78:79]
	v_pk_fma_f32 v[80:81], v[134:135], v[98:99], v[80:81]
	v_pk_fma_f32 v[82:83], v[132:133], v[98:99], v[82:83]
	v_pk_fma_f32 v[84:85], v[130:131], v[98:99], v[84:85]
	v_pk_fma_f32 v[86:87], v[128:129], v[98:99], v[86:87]
	v_pk_fma_f32 v[88:89], v[126:127], v[98:99], v[88:89]
	s_waitcnt vmcnt(19)
	v_lshlrev_b32_e32 v96, 16, v219
	v_and_b32_e32 v97, 0xffff0000, v219
	v_pk_fma_f32 v[172:173], v[158:159], v[96:97], v[172:173]
	v_pk_fma_f32 v[174:175], v[156:157], v[96:97], v[174:175]
	v_pk_fma_f32 v[176:177], v[154:155], v[96:97], v[176:177]
	v_pk_fma_f32 v[178:179], v[152:153], v[96:97], v[178:179]
	v_pk_fma_f32 v[180:181], v[150:151], v[96:97], v[180:181]
	v_pk_fma_f32 v[182:183], v[148:149], v[96:97], v[182:183]
	v_pk_fma_f32 v[184:185], v[146:147], v[96:97], v[184:185]
	v_pk_fma_f32 v[186:187], v[144:145], v[96:97], v[186:187]
	v_pk_fma_f32 v[188:189], v[142:143], v[96:97], v[188:189]
	v_pk_fma_f32 v[190:191], v[140:141], v[96:97], v[190:191]
	v_pk_fma_f32 v[78:79], v[138:139], v[96:97], v[78:79]
	v_pk_fma_f32 v[80:81], v[136:137], v[96:97], v[80:81]
	v_pk_fma_f32 v[82:83], v[134:135], v[96:97], v[82:83]
	v_pk_fma_f32 v[84:85], v[132:133], v[96:97], v[84:85]
	v_pk_fma_f32 v[86:87], v[130:131], v[96:97], v[86:87]
	v_pk_fma_f32 v[88:89], v[128:129], v[96:97], v[88:89]
	s_waitcnt vmcnt(18)
	v_lshlrev_b32_e32 v98, 16, v220
	v_and_b32_e32 v99, 0xffff0000, v220
	v_pk_fma_f32 v[172:173], v[160:161], v[98:99], v[172:173]
	v_pk_fma_f32 v[174:175], v[158:159], v[98:99], v[174:175]
	v_pk_fma_f32 v[176:177], v[156:157], v[98:99], v[176:177]
	v_pk_fma_f32 v[178:179], v[154:155], v[98:99], v[178:179]
	v_pk_fma_f32 v[180:181], v[152:153], v[98:99], v[180:181]
	v_pk_fma_f32 v[182:183], v[150:151], v[98:99], v[182:183]
	v_pk_fma_f32 v[184:185], v[148:149], v[98:99], v[184:185]
	v_pk_fma_f32 v[186:187], v[146:147], v[98:99], v[186:187]
	v_pk_fma_f32 v[188:189], v[144:145], v[98:99], v[188:189]
	v_pk_fma_f32 v[190:191], v[142:143], v[98:99], v[190:191]
	v_pk_fma_f32 v[78:79], v[140:141], v[98:99], v[78:79]
	v_pk_fma_f32 v[80:81], v[138:139], v[98:99], v[80:81]
	v_pk_fma_f32 v[82:83], v[136:137], v[98:99], v[82:83]
	v_pk_fma_f32 v[84:85], v[134:135], v[98:99], v[84:85]
	v_pk_fma_f32 v[86:87], v[132:133], v[98:99], v[86:87]
	v_pk_fma_f32 v[88:89], v[130:131], v[98:99], v[88:89]
	s_waitcnt vmcnt(17)
; __device__ __forceinline__ f32x2v bf2(unsigned v) { return (f32x2v){bflo(v), bfhi(v)}; }
; __device__ __forceinline__ void mixer_prompt_run(const Args& p, int run, int c2) {
;     ...
;             for (int i = 0; i < 38; ++i) {
;                 const int ti = t0 + 8 * hh - 30 + i; unsigned v = U32[(rowb + (ti >= 0 ? ti : 0)) * 256 + c2]; v = (ti >= 0) ? v : 0u; const f32x2v x = bf2(v);
; #pragma unroll
;                 for (int t = 0; t < 8; ++t) { const int j = i - t; if (j >= 0 && j <= 30) a[t] = w[j] * x + a[t]; }
;                 if (i == 18) asm volatile("" ::: "memory");
;             }
	v_lshlrev_b32_e32 v96, 16, v221
	v_and_b32_e32 v97, 0xffff0000, v221
	v_pk_fma_f32 v[172:173], v[162:163], v[96:97], v[172:173]
	v_pk_fma_f32 v[174:175], v[160:161], v[96:97], v[174:175]
	v_pk_fma_f32 v[176:177], v[158:159], v[96:97], v[176:177]
	v_pk_fma_f32 v[178:179], v[156:157], v[96:97], v[178:179]
	v_pk_fma_f32 v[180:181], v[154:155], v[96:97], v[180:181]
	v_pk_fma_f32 v[182:183], v[152:153], v[96:97], v[182:183]
	v_pk_fma_f32 v[184:185], v[150:151], v[96:97], v[184:185]
	v_pk_fma_f32 v[186:187], v[148:149], v[96:97], v[186:187]
	v_pk_fma_f32 v[188:189], v[146:147], v[96:97], v[188:189]
	v_pk_fma_f32 v[190:191], v[144:145], v[96:97], v[190:191]
	v_pk_fma_f32 v[78:79], v[142:143], v[96:97], v[78:79]
	v_pk_fma_f32 v[80:81], v[140:141], v[96:97], v[80:81]
	v_pk_fma_f32 v[82:83], v[138:139], v[96:97], v[82:83]
	v_pk_fma_f32 v[84:85], v[136:137], v[96:97], v[84:85]
	v_pk_fma_f32 v[86:87], v[134:135], v[96:97], v[86:87]
	v_pk_fma_f32 v[88:89], v[132:133], v[96:97], v[88:89]
	s_waitcnt vmcnt(16)
	v_lshlrev_b32_e32 v98, 16, v222
	v_and_b32_e32 v99, 0xffff0000, v222
	v_pk_fma_f32 v[172:173], v[168:169], v[98:99], v[172:173]
	v_pk_fma_f32 v[174:175], v[162:163], v[98:99], v[174:175]
	v_pk_fma_f32 v[176:177], v[160:161], v[98:99], v[176:177]
	v_pk_fma_f32 v[178:179], v[158:159], v[98:99], v[178:179]
	v_pk_fma_f32 v[180:181], v[156:157], v[98:99], v[180:181]
	v_pk_fma_f32 v[182:183], v[154:155], v[98:99], v[182:183]
	v_pk_fma_f32 v[184:185], v[152:153], v[98:99], v[184:185]
	v_pk_fma_f32 v[186:187], v[150:151], v[98:99], v[186:187]
	v_pk_fma_f32 v[188:189], v[148:149], v[98:99], v[188:189]
	v_pk_fma_f32 v[190:191], v[146:147], v[98:99], v[190:191]
	v_pk_fma_f32 v[78:79], v[144:145], v[98:99], v[78:79]
	v_pk_fma_f32 v[80:81], v[142:143], v[98:99], v[80:81]
	v_pk_fma_f32 v[82:83], v[140:141], v[98:99], v[82:83]
	v_pk_fma_f32 v[84:85], v[138:139], v[98:99], v[84:85]
	v_pk_fma_f32 v[86:87], v[136:137], v[98:99], v[86:87]
	v_pk_fma_f32 v[88:89], v[134:135], v[98:99], v[88:89]
.Lmx_row30:
	s_waitcnt vmcnt(15)
	v_lshlrev_b32_e32 v96, 16, v223
	v_and_b32_e32 v97, 0xffff0000, v223
	v_pk_fma_f32 v[172:173], v[170:171], v[96:97], v[172:173]
	v_pk_fma_f32 v[174:175], v[168:169], v[96:97], v[174:175]
	v_pk_fma_f32 v[176:177], v[162:163], v[96:97], v[176:177]
	v_pk_fma_f32 v[178:179], v[160:161], v[96:97], v[178:179]
	v_pk_fma_f32 v[180:181], v[158:159], v[96:97], v[180:181]
	v_pk_fma_f32 v[182:183], v[156:157], v[96:97], v[182:183]
	v_pk_fma_f32 v[184:185], v[154:155], v[96:97], v[184:185]
	v_pk_fma_f32 v[186:187], v[152:153], v[96:97], v[186:187]
	v_pk_fma_f32 v[188:189], v[150:151], v[96:97], v[188:189]
	v_pk_fma_f32 v[190:191], v[148:149], v[96:97], v[190:191]
	v_pk_fma_f32 v[78:79], v[146:147], v[96:97], v[78:79]
	v_pk_fma_f32 v[80:81], v[144:145], v[96:97], v[80:81]
	v_pk_fma_f32 v[82:83], v[142:143], v[96:97], v[82:83]
	v_pk_fma_f32 v[84:85], v[140:141], v[96:97], v[84:85]
	v_pk_fma_f32 v[86:87], v[138:139], v[96:97], v[86:87]
	v_pk_fma_f32 v[88:89], v[136:137], v[96:97], v[88:89]
	s_waitcnt vmcnt(14)
	v_lshlrev_b32_e32 v98, 16, v224
	v_and_b32_e32 v99, 0xffff0000, v224
	v_pk_fma_f32 v[174:175], v[170:171], v[98:99], v[174:175]
	v_pk_fma_f32 v[176:177], v[168:169], v[98:99], v[176:177]
	v_pk_fma_f32 v[178:179], v[162:163], v[98:99], v[178:179]
	v_pk_fma_f32 v[180:181], v[160:161], v[98:99], v[180:181]
	v_pk_fma_f32 v[182:183], v[158:159], v[98:99], v[182:183]
	v_pk_fma_f32 v[184:185], v[156:157], v[98:99], v[184:185]
	v_pk_fma_f32 v[186:187], v[154:155], v[98:99], v[186:187]
	v_pk_fma_f32 v[188:189], v[152:153], v[98:99], v[188:189]
	v_pk_fma_f32 v[190:191], v[150:151], v[98:99], v[190:191]
	v_pk_fma_f32 v[78:79], v[148:149], v[98:99], v[78:79]
	v_pk_fma_f32 v[80:81], v[146:147], v[98:99], v[80:81]
	v_pk_fma_f32 v[82:83], v[144:145], v[98:99], v[82:83]
	v_pk_fma_f32 v[84:85], v[142:143], v[98:99], v[84:85]
	v_pk_fma_f32 v[86:87], v[140:141], v[98:99], v[86:87]
	v_pk_fma_f32 v[88:89], v[138:139], v[98:99], v[88:89]
	s_waitcnt vmcnt(13)
	v_lshlrev_b32_e32 v96, 16, v225
	v_and_b32_e32 v97, 0xffff0000, v225
	v_pk_fma_f32 v[176:177], v[170:171], v[96:97], v[176:177]
	v_pk_fma_f32 v[178:179], v[168:169], v[96:97], v[178:179]
	v_pk_fma_f32 v[180:181], v[162:163], v[96:97], v[180:181]
	v_pk_fma_f32 v[182:183], v[160:161], v[96:97], v[182:183]
	v_pk_fma_f32 v[184:185], v[158:159], v[96:97], v[184:185]
	v_pk_fma_f32 v[186:187], v[156:157], v[96:97], v[186:187]
	v_pk_fma_f32 v[188:189], v[154:155], v[96:97], v[188:189]
	v_pk_fma_f32 v[190:191], v[152:153], v[96:97], v[190:191]
	v_pk_fma_f32 v[78:79], v[150:151], v[96:97], v[78:79]
	v_pk_fma_f32 v[80:81], v[148:149], v[96:97], v[80:81]
	v_pk_fma_f32 v[82:83], v[146:147], v[96:97], v[82:83]
	v_pk_fma_f32 v[84:85], v[144:145], v[96:97], v[84:85]
	v_pk_fma_f32 v[86:87], v[142:143], v[96:97], v[86:87]
	v_pk_fma_f32 v[88:89], v[140:141], v[96:97], v[88:89]
	s_waitcnt vmcnt(12)
	v_lshlrev_b32_e32 v98, 16, v226
	v_and_b32_e32 v99, 0xffff0000, v226
	v_pk_fma_f32 v[178:179], v[170:171], v[98:99], v[178:179]
	v_pk_fma_f32 v[180:181], v[168:169], v[98:99], v[180:181]
	v_pk_fma_f32 v[182:183], v[162:163], v[98:99], v[182:183]
	v_pk_fma_f32 v[184:185], v[160:161], v[98:99], v[184:185]
	v_pk_fma_f32 v[186:187], v[158:159], v[98:99], v[186:187]
	v_pk_fma_f32 v[188:189], v[156:157], v[98:99], v[188:189]
	v_pk_fma_f32 v[190:191], v[154:155], v[98:99], v[190:191]
	v_pk_fma_f32 v[78:79], v[152:153], v[98:99], v[78:79]
	v_pk_fma_f32 v[80:81], v[150:151], v[98:99], v[80:81]
	v_pk_fma_f32 v[82:83], v[148:149], v[98:99], v[82:83]
	v_pk_fma_f32 v[84:85], v[146:147], v[98:99], v[84:85]
	v_pk_fma_f32 v[86:87], v[144:145], v[98:99], v[86:87]
	v_pk_fma_f32 v[88:89], v[142:143], v[98:99], v[88:89]
	s_waitcnt vmcnt(11)
; __device__ __forceinline__ f32x2v bf2(unsigned v) { return (f32x2v){bflo(v), bfhi(v)}; }
; __device__ __forceinline__ void mixer_prompt_run(const Args& p, int run, int c2) {
;     ...
;             for (int i = 0; i < 38; ++i) {
;                 const int ti = t0 + 8 * hh - 30 + i; unsigned v = U32[(rowb + (ti >= 0 ? ti : 0)) * 256 + c2]; v = (ti >= 0) ? v : 0u; const f32x2v x = bf2(v);
; #pragma unroll
;                 for (int t = 0; t < 8; ++t) { const int j = i - t; if (j >= 0 && j <= 30) a[t] = w[j] * x + a[t]; }
;                 if (i == 18) asm volatile("" ::: "memory");
;             }
	v_lshlrev_b32_e32 v96, 16, v227
	v_and_b32_e32 v97, 0xffff0000, v227
	v_pk_fma_f32 v[180:181], v[170:171], v[96:97], v[180:181]
	v_pk_fma_f32 v[182:183], v[168:169], v[96:97], v[182:183]
	v_pk_fma_f32 v[184:185], v[162:163], v[96:97], v[184:185]
	v_pk_fma_f32 v[186:187], v[160:161], v[96:97], v[186:187]
	v_pk_fma_f32 v[188:189], v[158:159], v[96:97], v[188:189]
	v_pk_fma_f32 v[190:191], v[156:157], v[96:97], v[190:191]
	v_pk_fma_f32 v[78:79], v[154:155], v[96:97], v[78:79]
	v_pk_fma_f32 v[80:81], v[152:153], v[96:97], v[80:81]
	v_pk_fma_f32 v[82:83], v[150:151], v[96:97], v[82:83]
	v_pk_fma_f32 v[84:85], v[148:149], v[96:97], v[84:85]
	v_pk_fma_f32 v[86:87], v[146:147], v[96:97], v[86:87]
	v_pk_fma_f32 v[88:89], v[144:145], v[96:97], v[88:89]
	s_waitcnt vmcnt(10)
	v_lshlrev_b32_e32 v98, 16, v228
	v_and_b32_e32 v99, 0xffff0000, v228
	v_pk_fma_f32 v[182:183], v[170:171], v[98:99], v[182:183]
	v_pk_fma_f32 v[184:185], v[168:169], v[98:99], v[184:185]
	v_pk_fma_f32 v[186:187], v[162:163], v[98:99], v[186:187]
	v_pk_fma_f32 v[188:189], v[160:161], v[98:99], v[188:189]
	v_pk_fma_f32 v[190:191], v[158:159], v[98:99], v[190:191]
	v_pk_fma_f32 v[78:79], v[156:157], v[98:99], v[78:79]
	v_pk_fma_f32 v[80:81], v[154:155], v[98:99], v[80:81]
	v_pk_fma_f32 v[82:83], v[152:153], v[98:99], v[82:83]
	v_pk_fma_f32 v[84:85], v[150:151], v[98:99], v[84:85]
	v_pk_fma_f32 v[86:87], v[148:149], v[98:99], v[86:87]
	v_pk_fma_f32 v[88:89], v[146:147], v[98:99], v[88:89]
	s_waitcnt vmcnt(9)
	v_lshlrev_b32_e32 v96, 16, v229
	v_and_b32_e32 v97, 0xffff0000, v229
	v_pk_fma_f32 v[184:185], v[170:171], v[96:97], v[184:185]
	v_pk_fma_f32 v[186:187], v[168:169], v[96:97], v[186:187]
	v_pk_fma_f32 v[188:189], v[162:163], v[96:97], v[188:189]
	v_pk_fma_f32 v[190:191], v[160:161], v[96:97], v[190:191]
	v_pk_fma_f32 v[78:79], v[158:159], v[96:97], v[78:79]
	v_pk_fma_f32 v[80:81], v[156:157], v[96:97], v[80:81]
	v_pk_fma_f32 v[82:83], v[154:155], v[96:97], v[82:83]
	v_pk_fma_f32 v[84:85], v[152:153], v[96:97], v[84:85]
	v_pk_fma_f32 v[86:87], v[150:151], v[96:97], v[86:87]
	v_pk_fma_f32 v[88:89], v[148:149], v[96:97], v[88:89]
	s_waitcnt vmcnt(8)
	v_lshlrev_b32_e32 v98, 16, v230
	v_and_b32_e32 v99, 0xffff0000, v230
	v_pk_fma_f32 v[186:187], v[170:171], v[98:99], v[186:187]
	v_pk_fma_f32 v[188:189], v[168:169], v[98:99], v[188:189]
	v_pk_fma_f32 v[190:191], v[162:163], v[98:99], v[190:191]
	v_pk_fma_f32 v[78:79], v[160:161], v[98:99], v[78:79]
	v_pk_fma_f32 v[80:81], v[158:159], v[98:99], v[80:81]
	v_pk_fma_f32 v[82:83], v[156:157], v[98:99], v[82:83]
	v_pk_fma_f32 v[84:85], v[154:155], v[98:99], v[84:85]
	v_pk_fma_f32 v[86:87], v[152:153], v[98:99], v[86:87]
	v_pk_fma_f32 v[88:89], v[150:151], v[98:99], v[88:89]
	s_waitcnt vmcnt(7)
	v_lshlrev_b32_e32 v96, 16, v231
	v_and_b32_e32 v97, 0xffff0000, v231
	v_pk_fma_f32 v[188:189], v[170:171], v[96:97], v[188:189]
	v_pk_fma_f32 v[190:191], v[168:169], v[96:97], v[190:191]
	v_pk_fma_f32 v[78:79], v[162:163], v[96:97], v[78:79]
	v_pk_fma_f32 v[80:81], v[160:161], v[96:97], v[80:81]
	v_pk_fma_f32 v[82:83], v[158:159], v[96:97], v[82:83]
	v_pk_fma_f32 v[84:85], v[156:157], v[96:97], v[84:85]
	v_pk_fma_f32 v[86:87], v[154:155], v[96:97], v[86:87]
	v_pk_fma_f32 v[88:89], v[152:153], v[96:97], v[88:89]
	s_waitcnt vmcnt(6)
	v_lshlrev_b32_e32 v98, 16, v232
	v_and_b32_e32 v99, 0xffff0000, v232
	v_pk_fma_f32 v[190:191], v[170:171], v[98:99], v[190:191]
	v_pk_fma_f32 v[78:79], v[168:169], v[98:99], v[78:79]
	v_pk_fma_f32 v[80:81], v[162:163], v[98:99], v[80:81]
	v_pk_fma_f32 v[82:83], v[160:161], v[98:99], v[82:83]
	v_pk_fma_f32 v[84:85], v[158:159], v[98:99], v[84:85]
	v_pk_fma_f32 v[86:87], v[156:157], v[98:99], v[86:87]
	v_pk_fma_f32 v[88:89], v[154:155], v[98:99], v[88:89]
	s_waitcnt vmcnt(5)
	v_lshlrev_b32_e32 v96, 16, v233
	v_and_b32_e32 v97, 0xffff0000, v233
	v_pk_fma_f32 v[78:79], v[170:171], v[96:97], v[78:79]
	v_pk_fma_f32 v[80:81], v[168:169], v[96:97], v[80:81]
	v_pk_fma_f32 v[82:83], v[162:163], v[96:97], v[82:83]
	v_pk_fma_f32 v[84:85], v[160:161], v[96:97], v[84:85]
	v_pk_fma_f32 v[86:87], v[158:159], v[96:97], v[86:87]
	v_pk_fma_f32 v[88:89], v[156:157], v[96:97], v[88:89]
	s_waitcnt vmcnt(4)
	v_lshlrev_b32_e32 v98, 16, v234
	v_and_b32_e32 v99, 0xffff0000, v234
	v_pk_fma_f32 v[80:81], v[170:171], v[98:99], v[80:81]
	v_pk_fma_f32 v[82:83], v[168:169], v[98:99], v[82:83]
	v_pk_fma_f32 v[84:85], v[162:163], v[98:99], v[84:85]
	v_pk_fma_f32 v[86:87], v[160:161], v[98:99], v[86:87]
	v_pk_fma_f32 v[88:89], v[158:159], v[98:99], v[88:89]
	s_waitcnt vmcnt(3)
	v_lshlrev_b32_e32 v96, 16, v235
	v_and_b32_e32 v97, 0xffff0000, v235
	v_pk_fma_f32 v[82:83], v[170:171], v[96:97], v[82:83]
	v_pk_fma_f32 v[84:85], v[168:169], v[96:97], v[84:85]
	v_pk_fma_f32 v[86:87], v[162:163], v[96:97], v[86:87]
	v_pk_fma_f32 v[88:89], v[160:161], v[96:97], v[88:89]
	s_waitcnt vmcnt(2)
	v_lshlrev_b32_e32 v98, 16, v236
	v_and_b32_e32 v99, 0xffff0000, v236
	v_pk_fma_f32 v[84:85], v[170:171], v[98:99], v[84:85]
	v_pk_fma_f32 v[86:87], v[168:169], v[98:99], v[86:87]
	v_pk_fma_f32 v[88:89], v[162:163], v[98:99], v[88:89]
	s_waitcnt vmcnt(1)
	v_lshlrev_b32_e32 v96, 16, v237
	v_and_b32_e32 v97, 0xffff0000, v237
	v_pk_fma_f32 v[86:87], v[170:171], v[96:97], v[86:87]
	v_pk_fma_f32 v[88:89], v[168:169], v[96:97], v[88:89]
	s_waitcnt vmcnt(0)
; template <int CTRL> __device__ __forceinline__ float dpp_mov(float v) { return __builtin_bit_cast(float, __builtin_amdgcn_update_dpp(0, __builtin_bit_cast(int, v), CTRL, 0xf, 0xf, true)); }
; __device__ __forceinline__ f32x2v bf2(unsigned v) { return (f32x2v){bflo(v), bfhi(v)}; }
; __device__ __forceinline__ float half_wave_sum(float v) {
;     v += dpp_mov<0xB1>(v);
;     v += dpp_mov<0x4E>(v);
;     v += dpp_mov<0x141>(v);
;     v += dpp_mov<0x140>(v);
;     v += __shfl_xor(v, 16);
;     return v;
; }
; __device__ __forceinline__ void gn_swish_store(float v0, float v1, f32x2v gg, f32x2v gb, unsigned* dst) {
;     const float mean = half_wave_sum(v0 + v1) * (1.0f / 64.0f); const float d0 = v0 - mean, d1 = v1 - mean;
;     const float rstd = rsqrtf(half_wave_sum(d0 * d0 + d1 * d1) * (1.0f / 64.0f) + LN_EPS);
; __device__ __forceinline__ void mixer_prompt_run(const Args& p, int run, int c2) {
;     ...
;                 const int ti = t0 + 8 * hh - 30 + i; unsigned v = U32[(rowb + (ti >= 0 ? ti : 0)) * 256 + c2]; v = (ti >= 0) ? v : 0u; const f32x2v x = bf2(v);
; #pragma unroll
;                 for (int t = 0; t < 8; ++t) { const int j = i - t; if (j >= 0 && j <= 30) a[t] = w[j] * x + a[t]; }
;                 if (i == 18) asm volatile("" ::: "memory");
;             }
; #pragma unroll
;             for (int t = 0; t < 8; ++t) gn_swish_store(a[t].x, a[t].y, gg, gb, M32 + (rowb + t0 + 8 * hh + t) * 512 + c2);
	v_lshlrev_b32_e32 v98, 16, v238
	v_and_b32_e32 v99, 0xffff0000, v238
	v_pk_fma_f32 v[88:89], v[170:171], v[98:99], v[88:89]
	v_add_f32_e32 v194, v172, v173
	v_add_f32_e32 v198, v174, v175
	v_add_f32_e32 v202, v176, v177
	v_add_f32_e32 v206, v178, v179
	v_add_f32_e32 v210, v180, v181
	v_add_f32_e32 v214, v182, v183
	v_add_f32_e32 v218, v184, v185
	v_add_f32_e32 v222, v186, v187
	v_add_f32_dpp v194, v194, v194 quad_perm:[1,0,3,2] row_mask:0xf bank_mask:0xf bound_ctrl:1
	v_add_f32_dpp v198, v198, v198 quad_perm:[1,0,3,2] row_mask:0xf bank_mask:0xf bound_ctrl:1
	v_add_f32_dpp v202, v202, v202 quad_perm:[1,0,3,2] row_mask:0xf bank_mask:0xf bound_ctrl:1
	v_add_f32_dpp v206, v206, v206 quad_perm:[1,0,3,2] row_mask:0xf bank_mask:0xf bound_ctrl:1
	v_add_f32_dpp v210, v210, v210 quad_perm:[1,0,3,2] row_mask:0xf bank_mask:0xf bound_ctrl:1
	v_add_f32_dpp v214, v214, v214 quad_perm:[1,0,3,2] row_mask:0xf bank_mask:0xf bound_ctrl:1
	v_add_f32_dpp v218, v218, v218 quad_perm:[1,0,3,2] row_mask:0xf bank_mask:0xf bound_ctrl:1
	v_add_f32_dpp v222, v222, v222 quad_perm:[1,0,3,2] row_mask:0xf bank_mask:0xf bound_ctrl:1
	v_add_f32_dpp v194, v194, v194 quad_perm:[2,3,0,1] row_mask:0xf bank_mask:0xf bound_ctrl:1
	v_add_f32_dpp v198, v198, v198 quad_perm:[2,3,0,1] row_mask:0xf bank_mask:0xf bound_ctrl:1
	v_add_f32_dpp v202, v202, v202 quad_perm:[2,3,0,1] row_mask:0xf bank_mask:0xf bound_ctrl:1
	v_add_f32_dpp v206, v206, v206 quad_perm:[2,3,0,1] row_mask:0xf bank_mask:0xf bound_ctrl:1
	v_add_f32_dpp v210, v210, v210 quad_perm:[2,3,0,1] row_mask:0xf bank_mask:0xf bound_ctrl:1
	v_add_f32_dpp v214, v214, v214 quad_perm:[2,3,0,1] row_mask:0xf bank_mask:0xf bound_ctrl:1
	v_add_f32_dpp v218, v218, v218 quad_perm:[2,3,0,1] row_mask:0xf bank_mask:0xf bound_ctrl:1
	v_add_f32_dpp v222, v222, v222 quad_perm:[2,3,0,1] row_mask:0xf bank_mask:0xf bound_ctrl:1
	v_add_f32_dpp v194, v194, v194 row_half_mirror row_mask:0xf bank_mask:0xf bound_ctrl:1
	v_add_f32_dpp v198, v198, v198 row_half_mirror row_mask:0xf bank_mask:0xf bound_ctrl:1
	v_add_f32_dpp v202, v202, v202 row_half_mirror row_mask:0xf bank_mask:0xf bound_ctrl:1
	v_add_f32_dpp v206, v206, v206 row_half_mirror row_mask:0xf bank_mask:0xf bound_ctrl:1
	v_add_f32_dpp v210, v210, v210 row_half_mirror row_mask:0xf bank_mask:0xf bound_ctrl:1
	v_add_f32_dpp v214, v214, v214 row_half_mirror row_mask:0xf bank_mask:0xf bound_ctrl:1
	v_add_f32_dpp v218, v218, v218 row_half_mirror row_mask:0xf bank_mask:0xf bound_ctrl:1
	v_add_f32_dpp v222, v222, v222 row_half_mirror row_mask:0xf bank_mask:0xf bound_ctrl:1
	v_add_f32_dpp v194, v194, v194 row_mirror row_mask:0xf bank_mask:0xf bound_ctrl:1
	v_add_f32_dpp v198, v198, v198 row_mirror row_mask:0xf bank_mask:0xf bound_ctrl:1
	v_add_f32_dpp v202, v202, v202 row_mirror row_mask:0xf bank_mask:0xf bound_ctrl:1
	v_add_f32_dpp v206, v206, v206 row_mirror row_mask:0xf bank_mask:0xf bound_ctrl:1
	v_add_f32_dpp v210, v210, v210 row_mirror row_mask:0xf bank_mask:0xf bound_ctrl:1
	v_add_f32_dpp v214, v214, v214 row_mirror row_mask:0xf bank_mask:0xf bound_ctrl:1
	v_add_f32_dpp v218, v218, v218 row_mirror row_mask:0xf bank_mask:0xf bound_ctrl:1
	v_add_f32_dpp v222, v222, v222 row_mirror row_mask:0xf bank_mask:0xf bound_ctrl:1
	ds_bpermute_b32 v195, v239, v194
	ds_bpermute_b32 v199, v239, v198
	ds_bpermute_b32 v203, v239, v202
	ds_bpermute_b32 v207, v239, v206
	ds_bpermute_b32 v211, v239, v210
	ds_bpermute_b32 v215, v239, v214
	ds_bpermute_b32 v219, v239, v218
	ds_bpermute_b32 v223, v239, v222
	s_waitcnt lgkmcnt(7)
	v_add_f32_e32 v194, v194, v195
	s_waitcnt lgkmcnt(6)
	v_add_f32_e32 v198, v198, v199
	s_waitcnt lgkmcnt(5)
	v_add_f32_e32 v202, v202, v203
	s_waitcnt lgkmcnt(4)
	v_add_f32_e32 v206, v206, v207
	s_waitcnt lgkmcnt(3)
	v_add_f32_e32 v210, v210, v211
	s_waitcnt lgkmcnt(2)
	v_add_f32_e32 v214, v214, v215
	s_waitcnt lgkmcnt(1)
	v_add_f32_e32 v218, v218, v219
	s_waitcnt lgkmcnt(0)
	v_add_f32_e32 v222, v222, v223
	v_pk_fma_f32 v[172:173], v[194:195], s[78:79], v[172:173] op_sel_hi:[0,1,1]
	v_pk_fma_f32 v[174:175], v[198:199], s[78:79], v[174:175] op_sel_hi:[0,1,1]
	v_pk_fma_f32 v[176:177], v[202:203], s[78:79], v[176:177] op_sel_hi:[0,1,1]
	v_pk_fma_f32 v[178:179], v[206:207], s[78:79], v[178:179] op_sel_hi:[0,1,1]
	v_pk_fma_f32 v[180:181], v[210:211], s[78:79], v[180:181] op_sel_hi:[0,1,1]
	v_pk_fma_f32 v[182:183], v[214:215], s[78:79], v[182:183] op_sel_hi:[0,1,1]
	v_pk_fma_f32 v[184:185], v[218:219], s[78:79], v[184:185] op_sel_hi:[0,1,1]
	v_pk_fma_f32 v[186:187], v[222:223], s[78:79], v[186:187] op_sel_hi:[0,1,1]
	v_pk_mul_f32 v[196:197], v[172:173], v[172:173]
	v_pk_mul_f32 v[200:201], v[174:175], v[174:175]
	v_pk_mul_f32 v[204:205], v[176:177], v[176:177]
	v_pk_mul_f32 v[208:209], v[178:179], v[178:179]
	v_pk_mul_f32 v[212:213], v[180:181], v[180:181]
	v_pk_mul_f32 v[216:217], v[182:183], v[182:183]
	v_pk_mul_f32 v[220:221], v[184:185], v[184:185]
	v_pk_mul_f32 v[224:225], v[186:187], v[186:187]
	v_add_f32_e32 v194, v196, v197
	v_add_f32_e32 v198, v200, v201
	v_add_f32_e32 v202, v204, v205
	v_add_f32_e32 v206, v208, v209
	v_add_f32_e32 v210, v212, v213
	v_add_f32_e32 v214, v216, v217
	v_add_f32_e32 v218, v220, v221
	v_add_f32_e32 v222, v224, v225
	v_add_f32_dpp v194, v194, v194 quad_perm:[1,0,3,2] row_mask:0xf bank_mask:0xf bound_ctrl:1
	v_add_f32_dpp v198, v198, v198 quad_perm:[1,0,3,2] row_mask:0xf bank_mask:0xf bound_ctrl:1
	v_add_f32_dpp v202, v202, v202 quad_perm:[1,0,3,2] row_mask:0xf bank_mask:0xf bound_ctrl:1
	v_add_f32_dpp v206, v206, v206 quad_perm:[1,0,3,2] row_mask:0xf bank_mask:0xf bound_ctrl:1
	v_add_f32_dpp v210, v210, v210 quad_perm:[1,0,3,2] row_mask:0xf bank_mask:0xf bound_ctrl:1
; __device__ __forceinline__ float fsigmoid(float x) { return __builtin_amdgcn_rcpf(1.0f + __expf(-x)); }
; __device__ __forceinline__ void gn_swish_store(float v0, float v1, f32x2v gg, f32x2v gb, unsigned* dst) {
;     ...
;     const float rstd = rsqrtf(half_wave_sum(d0 * d0 + d1 * d1) * (1.0f / 64.0f) + LN_EPS);
;     float y0 = d0 * rstd * gg.x + gb.x, y1 = d1 * rstd * gg.y + gb.y;
;     y0 = y0 * fsigmoid(y0); y1 = y1 * fsigmoid(y1);
	v_add_f32_dpp v214, v214, v214 quad_perm:[1,0,3,2] row_mask:0xf bank_mask:0xf bound_ctrl:1
	v_add_f32_dpp v218, v218, v218 quad_perm:[1,0,3,2] row_mask:0xf bank_mask:0xf bound_ctrl:1
	v_add_f32_dpp v222, v222, v222 quad_perm:[1,0,3,2] row_mask:0xf bank_mask:0xf bound_ctrl:1
	v_add_f32_dpp v194, v194, v194 quad_perm:[2,3,0,1] row_mask:0xf bank_mask:0xf bound_ctrl:1
	v_add_f32_dpp v198, v198, v198 quad_perm:[2,3,0,1] row_mask:0xf bank_mask:0xf bound_ctrl:1
	v_add_f32_dpp v202, v202, v202 quad_perm:[2,3,0,1] row_mask:0xf bank_mask:0xf bound_ctrl:1
	v_add_f32_dpp v206, v206, v206 quad_perm:[2,3,0,1] row_mask:0xf bank_mask:0xf bound_ctrl:1
	v_add_f32_dpp v210, v210, v210 quad_perm:[2,3,0,1] row_mask:0xf bank_mask:0xf bound_ctrl:1
	v_add_f32_dpp v214, v214, v214 quad_perm:[2,3,0,1] row_mask:0xf bank_mask:0xf bound_ctrl:1
	v_add_f32_dpp v218, v218, v218 quad_perm:[2,3,0,1] row_mask:0xf bank_mask:0xf bound_ctrl:1
	v_add_f32_dpp v222, v222, v222 quad_perm:[2,3,0,1] row_mask:0xf bank_mask:0xf bound_ctrl:1
	v_add_f32_dpp v194, v194, v194 row_half_mirror row_mask:0xf bank_mask:0xf bound_ctrl:1
	v_add_f32_dpp v198, v198, v198 row_half_mirror row_mask:0xf bank_mask:0xf bound_ctrl:1
	v_add_f32_dpp v202, v202, v202 row_half_mirror row_mask:0xf bank_mask:0xf bound_ctrl:1
	v_add_f32_dpp v206, v206, v206 row_half_mirror row_mask:0xf bank_mask:0xf bound_ctrl:1
	v_add_f32_dpp v210, v210, v210 row_half_mirror row_mask:0xf bank_mask:0xf bound_ctrl:1
	v_add_f32_dpp v214, v214, v214 row_half_mirror row_mask:0xf bank_mask:0xf bound_ctrl:1
	v_add_f32_dpp v218, v218, v218 row_half_mirror row_mask:0xf bank_mask:0xf bound_ctrl:1
	v_add_f32_dpp v222, v222, v222 row_half_mirror row_mask:0xf bank_mask:0xf bound_ctrl:1
	v_add_f32_dpp v194, v194, v194 row_mirror row_mask:0xf bank_mask:0xf bound_ctrl:1
	v_add_f32_dpp v198, v198, v198 row_mirror row_mask:0xf bank_mask:0xf bound_ctrl:1
	v_add_f32_dpp v202, v202, v202 row_mirror row_mask:0xf bank_mask:0xf bound_ctrl:1
	v_add_f32_dpp v206, v206, v206 row_mirror row_mask:0xf bank_mask:0xf bound_ctrl:1
	v_add_f32_dpp v210, v210, v210 row_mirror row_mask:0xf bank_mask:0xf bound_ctrl:1
	v_add_f32_dpp v214, v214, v214 row_mirror row_mask:0xf bank_mask:0xf bound_ctrl:1
	v_add_f32_dpp v218, v218, v218 row_mirror row_mask:0xf bank_mask:0xf bound_ctrl:1
	v_add_f32_dpp v222, v222, v222 row_mirror row_mask:0xf bank_mask:0xf bound_ctrl:1
	ds_bpermute_b32 v195, v239, v194
	ds_bpermute_b32 v199, v239, v198
	ds_bpermute_b32 v203, v239, v202
	ds_bpermute_b32 v207, v239, v206
	ds_bpermute_b32 v211, v239, v210
	ds_bpermute_b32 v215, v239, v214
	ds_bpermute_b32 v219, v239, v218
	ds_bpermute_b32 v223, v239, v222
	s_waitcnt lgkmcnt(7)
	v_add_f32_e32 v194, v194, v195
	s_waitcnt lgkmcnt(6)
	v_add_f32_e32 v198, v198, v199
	s_waitcnt lgkmcnt(5)
	v_add_f32_e32 v202, v202, v203
	s_waitcnt lgkmcnt(4)
	v_add_f32_e32 v206, v206, v207
	s_waitcnt lgkmcnt(3)
	v_add_f32_e32 v210, v210, v211
	s_waitcnt lgkmcnt(2)
	v_add_f32_e32 v214, v214, v215
	s_waitcnt lgkmcnt(1)
	v_add_f32_e32 v218, v218, v219
	s_waitcnt lgkmcnt(0)
	v_add_f32_e32 v222, v222, v223
	v_fma_f32 v194, v194, s48, v241
	v_fma_f32 v198, v198, s48, v241
	v_fma_f32 v202, v202, s48, v241
	v_fma_f32 v206, v206, s48, v241
	v_fma_f32 v210, v210, s48, v241
	v_fma_f32 v214, v214, s48, v241
	v_fma_f32 v218, v218, s48, v241
	v_fma_f32 v222, v222, s48, v241
	v_rsq_f32_e32 v194, v194
	v_rsq_f32_e32 v198, v198
	v_rsq_f32_e32 v202, v202
	v_rsq_f32_e32 v206, v206
	v_rsq_f32_e32 v210, v210
	v_rsq_f32_e32 v214, v214
	v_rsq_f32_e32 v218, v218
	v_rsq_f32_e32 v222, v222
	v_pk_mul_f32 v[172:173], v[172:173], v[194:195] op_sel_hi:[1,0]
	v_pk_mul_f32 v[174:175], v[174:175], v[198:199] op_sel_hi:[1,0]
	v_pk_mul_f32 v[176:177], v[176:177], v[202:203] op_sel_hi:[1,0]
	v_pk_mul_f32 v[178:179], v[178:179], v[206:207] op_sel_hi:[1,0]
	v_pk_mul_f32 v[180:181], v[180:181], v[210:211] op_sel_hi:[1,0]
	v_pk_mul_f32 v[182:183], v[182:183], v[214:215] op_sel_hi:[1,0]
	v_pk_mul_f32 v[184:185], v[184:185], v[218:219] op_sel_hi:[1,0]
	v_pk_mul_f32 v[186:187], v[186:187], v[222:223] op_sel_hi:[1,0]
	v_pk_fma_f32 v[172:173], v[172:173], v[92:93], v[94:95]
	v_pk_fma_f32 v[174:175], v[174:175], v[92:93], v[94:95]
	v_pk_fma_f32 v[176:177], v[176:177], v[92:93], v[94:95]
	v_pk_fma_f32 v[178:179], v[178:179], v[92:93], v[94:95]
	v_pk_fma_f32 v[180:181], v[180:181], v[92:93], v[94:95]
	v_pk_fma_f32 v[182:183], v[182:183], v[92:93], v[94:95]
	v_pk_fma_f32 v[184:185], v[184:185], v[92:93], v[94:95]
	v_pk_fma_f32 v[186:187], v[186:187], v[92:93], v[94:95]
	v_pk_mul_f32 v[196:197], v[172:173], s[80:81]
	v_pk_mul_f32 v[200:201], v[174:175], s[80:81]
	v_pk_mul_f32 v[204:205], v[176:177], s[80:81]
	v_pk_mul_f32 v[208:209], v[178:179], s[80:81]
	v_pk_mul_f32 v[212:213], v[180:181], s[80:81]
	v_pk_mul_f32 v[216:217], v[182:183], s[80:81]
	v_pk_mul_f32 v[220:221], v[184:185], s[80:81]
	v_pk_mul_f32 v[224:225], v[186:187], s[80:81]
	v_exp_f32_e32 v196, v196
	v_exp_f32_e32 v197, v197
	v_exp_f32_e32 v200, v200
	v_exp_f32_e32 v201, v201
	v_exp_f32_e32 v204, v204
	v_exp_f32_e32 v205, v205
	v_exp_f32_e32 v208, v208
	v_exp_f32_e32 v209, v209
	v_exp_f32_e32 v212, v212
	v_exp_f32_e32 v213, v213
	v_exp_f32_e32 v216, v216
	v_exp_f32_e32 v217, v217
	v_exp_f32_e32 v220, v220
	v_exp_f32_e32 v221, v221
	v_exp_f32_e32 v224, v224
	v_exp_f32_e32 v225, v225
	v_pk_add_f32 v[196:197], v[196:197], s[86:87]
	v_pk_add_f32 v[200:201], v[200:201], s[86:87]
	v_pk_add_f32 v[204:205], v[204:205], s[86:87]
	v_pk_add_f32 v[208:209], v[208:209], s[86:87]
	v_pk_add_f32 v[212:213], v[212:213], s[86:87]
	v_pk_add_f32 v[216:217], v[216:217], s[86:87]
	v_pk_add_f32 v[220:221], v[220:221], s[86:87]
; __device__ __forceinline__ unsigned pk2(float lo, float hi) { f32x2v v = {lo, hi}; b16x2v b = __builtin_convertvector(v, b16x2v); return __builtin_bit_cast(unsigned, b); }
; __device__ __forceinline__ float fsigmoid(float x) { return __builtin_amdgcn_rcpf(1.0f + __expf(-x)); }
; __device__ __forceinline__ void gn_swish_store(float v0, float v1, f32x2v gg, f32x2v gb, unsigned* dst) {
;     const float mean = half_wave_sum(v0 + v1) * (1.0f / 64.0f); const float d0 = v0 - mean, d1 = v1 - mean;
;     const float rstd = rsqrtf(half_wave_sum(d0 * d0 + d1 * d1) * (1.0f / 64.0f) + LN_EPS);
;     ...
;     y0 = y0 * fsigmoid(y0); y1 = y1 * fsigmoid(y1);
;     *dst = pk2(y0, y1);
; __device__ __forceinline__ void mixer_prompt_run(const Args& p, int run, int c2) {
;     ...
;             for (int t = 0; t < 8; ++t) gn_swish_store(a[t].x, a[t].y, gg, gb, M32 + (rowb + t0 + 8 * hh + t) * 512 + c2);
	v_pk_add_f32 v[224:225], v[224:225], s[86:87]
	v_rcp_f32_e32 v196, v196
	v_rcp_f32_e32 v197, v197
	v_rcp_f32_e32 v200, v200
	v_rcp_f32_e32 v201, v201
	v_rcp_f32_e32 v204, v204
	v_rcp_f32_e32 v205, v205
	v_rcp_f32_e32 v208, v208
	v_rcp_f32_e32 v209, v209
	v_rcp_f32_e32 v212, v212
	v_rcp_f32_e32 v213, v213
	v_rcp_f32_e32 v216, v216
	v_rcp_f32_e32 v217, v217
	v_rcp_f32_e32 v220, v220
	v_rcp_f32_e32 v221, v221
	v_rcp_f32_e32 v224, v224
	v_rcp_f32_e32 v225, v225
	v_pk_mul_f32 v[172:173], v[172:173], v[196:197]
	v_pk_mul_f32 v[174:175], v[174:175], v[200:201]
	v_pk_mul_f32 v[176:177], v[176:177], v[204:205]
	v_pk_mul_f32 v[178:179], v[178:179], v[208:209]
	v_pk_mul_f32 v[180:181], v[180:181], v[212:213]
	v_pk_mul_f32 v[182:183], v[182:183], v[216:217]
	v_pk_mul_f32 v[184:185], v[184:185], v[220:221]
	v_pk_mul_f32 v[186:187], v[186:187], v[224:225]
	v_cvt_pk_bf16_f32 v194, v172, v173
	v_cvt_pk_bf16_f32 v198, v174, v175
	v_cvt_pk_bf16_f32 v202, v176, v177
	v_cvt_pk_bf16_f32 v206, v178, v179
	v_cvt_pk_bf16_f32 v210, v180, v181
	v_cvt_pk_bf16_f32 v214, v182, v183
	v_cvt_pk_bf16_f32 v218, v184, v185
	v_cvt_pk_bf16_f32 v222, v186, v187
	global_store_dword v105, v194, s[70:71] offset:-4096
	global_store_dword v105, v198, s[70:71] offset:-2048
	global_store_dword v105, v202, s[70:71] offset:0
	global_store_dword v105, v206, s[70:71] offset:2048
	s_add_u32 s70, s70, 0x2000
	s_addc_u32 s71, s71, 0
	global_store_dword v105, v210, s[70:71] offset:-4096
	global_store_dword v105, v214, s[70:71] offset:-2048
	global_store_dword v105, v218, s[70:71] offset:0
	global_store_dword v105, v222, s[70:71] offset:2048
	v_add_f32_e32 v194, v188, v189
	v_add_f32_e32 v198, v190, v191
	v_add_f32_e32 v202, v78, v79
	v_add_f32_e32 v206, v80, v81
	v_add_f32_e32 v210, v82, v83
	v_add_f32_e32 v214, v84, v85
	v_add_f32_e32 v218, v86, v87
	v_add_f32_e32 v222, v88, v89
	v_add_f32_dpp v194, v194, v194 quad_perm:[1,0,3,2] row_mask:0xf bank_mask:0xf bound_ctrl:1
	v_add_f32_dpp v198, v198, v198 quad_perm:[1,0,3,2] row_mask:0xf bank_mask:0xf bound_ctrl:1
	v_add_f32_dpp v202, v202, v202 quad_perm:[1,0,3,2] row_mask:0xf bank_mask:0xf bound_ctrl:1
	v_add_f32_dpp v206, v206, v206 quad_perm:[1,0,3,2] row_mask:0xf bank_mask:0xf bound_ctrl:1
	v_add_f32_dpp v210, v210, v210 quad_perm:[1,0,3,2] row_mask:0xf bank_mask:0xf bound_ctrl:1
	v_add_f32_dpp v214, v214, v214 quad_perm:[1,0,3,2] row_mask:0xf bank_mask:0xf bound_ctrl:1
	v_add_f32_dpp v218, v218, v218 quad_perm:[1,0,3,2] row_mask:0xf bank_mask:0xf bound_ctrl:1
	v_add_f32_dpp v222, v222, v222 quad_perm:[1,0,3,2] row_mask:0xf bank_mask:0xf bound_ctrl:1
	v_add_f32_dpp v194, v194, v194 quad_perm:[2,3,0,1] row_mask:0xf bank_mask:0xf bound_ctrl:1
	v_add_f32_dpp v198, v198, v198 quad_perm:[2,3,0,1] row_mask:0xf bank_mask:0xf bound_ctrl:1
	v_add_f32_dpp v202, v202, v202 quad_perm:[2,3,0,1] row_mask:0xf bank_mask:0xf bound_ctrl:1
	v_add_f32_dpp v206, v206, v206 quad_perm:[2,3,0,1] row_mask:0xf bank_mask:0xf bound_ctrl:1
	v_add_f32_dpp v210, v210, v210 quad_perm:[2,3,0,1] row_mask:0xf bank_mask:0xf bound_ctrl:1
	v_add_f32_dpp v214, v214, v214 quad_perm:[2,3,0,1] row_mask:0xf bank_mask:0xf bound_ctrl:1
	v_add_f32_dpp v218, v218, v218 quad_perm:[2,3,0,1] row_mask:0xf bank_mask:0xf bound_ctrl:1
	v_add_f32_dpp v222, v222, v222 quad_perm:[2,3,0,1] row_mask:0xf bank_mask:0xf bound_ctrl:1
	v_add_f32_dpp v194, v194, v194 row_half_mirror row_mask:0xf bank_mask:0xf bound_ctrl:1
	v_add_f32_dpp v198, v198, v198 row_half_mirror row_mask:0xf bank_mask:0xf bound_ctrl:1
	v_add_f32_dpp v202, v202, v202 row_half_mirror row_mask:0xf bank_mask:0xf bound_ctrl:1
	v_add_f32_dpp v206, v206, v206 row_half_mirror row_mask:0xf bank_mask:0xf bound_ctrl:1
	v_add_f32_dpp v210, v210, v210 row_half_mirror row_mask:0xf bank_mask:0xf bound_ctrl:1
	v_add_f32_dpp v214, v214, v214 row_half_mirror row_mask:0xf bank_mask:0xf bound_ctrl:1
	v_add_f32_dpp v218, v218, v218 row_half_mirror row_mask:0xf bank_mask:0xf bound_ctrl:1
	v_add_f32_dpp v222, v222, v222 row_half_mirror row_mask:0xf bank_mask:0xf bound_ctrl:1
	v_add_f32_dpp v194, v194, v194 row_mirror row_mask:0xf bank_mask:0xf bound_ctrl:1
	v_add_f32_dpp v198, v198, v198 row_mirror row_mask:0xf bank_mask:0xf bound_ctrl:1
	v_add_f32_dpp v202, v202, v202 row_mirror row_mask:0xf bank_mask:0xf bound_ctrl:1
	v_add_f32_dpp v206, v206, v206 row_mirror row_mask:0xf bank_mask:0xf bound_ctrl:1
	v_add_f32_dpp v210, v210, v210 row_mirror row_mask:0xf bank_mask:0xf bound_ctrl:1
	v_add_f32_dpp v214, v214, v214 row_mirror row_mask:0xf bank_mask:0xf bound_ctrl:1
	v_add_f32_dpp v218, v218, v218 row_mirror row_mask:0xf bank_mask:0xf bound_ctrl:1
	v_add_f32_dpp v222, v222, v222 row_mirror row_mask:0xf bank_mask:0xf bound_ctrl:1
	ds_bpermute_b32 v195, v239, v194
	ds_bpermute_b32 v199, v239, v198
	ds_bpermute_b32 v203, v239, v202
	ds_bpermute_b32 v207, v239, v206
	ds_bpermute_b32 v211, v239, v210
	ds_bpermute_b32 v215, v239, v214
	ds_bpermute_b32 v219, v239, v218
	ds_bpermute_b32 v223, v239, v222
	s_waitcnt lgkmcnt(7)
	v_add_f32_e32 v194, v194, v195
	s_waitcnt lgkmcnt(6)
	v_add_f32_e32 v198, v198, v199
	s_waitcnt lgkmcnt(5)
	v_add_f32_e32 v202, v202, v203
	s_waitcnt lgkmcnt(4)
	v_add_f32_e32 v206, v206, v207
	s_waitcnt lgkmcnt(3)
	v_add_f32_e32 v210, v210, v211
	s_waitcnt lgkmcnt(2)
	v_add_f32_e32 v214, v214, v215
	s_waitcnt lgkmcnt(1)
	v_add_f32_e32 v218, v218, v219
	s_waitcnt lgkmcnt(0)
; __device__ __forceinline__ void gn_swish_store(float v0, float v1, f32x2v gg, f32x2v gb, unsigned* dst) {
;     const float mean = half_wave_sum(v0 + v1) * (1.0f / 64.0f); const float d0 = v0 - mean, d1 = v1 - mean;
;     const float rstd = rsqrtf(half_wave_sum(d0 * d0 + d1 * d1) * (1.0f / 64.0f) + LN_EPS);
	v_add_f32_e32 v222, v222, v223
	v_pk_fma_f32 v[188:189], v[194:195], s[78:79], v[188:189] op_sel_hi:[0,1,1]
	v_pk_fma_f32 v[190:191], v[198:199], s[78:79], v[190:191] op_sel_hi:[0,1,1]
	v_pk_fma_f32 v[78:79], v[202:203], s[78:79], v[78:79] op_sel_hi:[0,1,1]
	v_pk_fma_f32 v[80:81], v[206:207], s[78:79], v[80:81] op_sel_hi:[0,1,1]
	v_pk_fma_f32 v[82:83], v[210:211], s[78:79], v[82:83] op_sel_hi:[0,1,1]
	v_pk_fma_f32 v[84:85], v[214:215], s[78:79], v[84:85] op_sel_hi:[0,1,1]
	v_pk_fma_f32 v[86:87], v[218:219], s[78:79], v[86:87] op_sel_hi:[0,1,1]
	v_pk_fma_f32 v[88:89], v[222:223], s[78:79], v[88:89] op_sel_hi:[0,1,1]
	v_pk_mul_f32 v[196:197], v[188:189], v[188:189]
	v_pk_mul_f32 v[200:201], v[190:191], v[190:191]
	v_pk_mul_f32 v[204:205], v[78:79], v[78:79]
	v_pk_mul_f32 v[208:209], v[80:81], v[80:81]
	v_pk_mul_f32 v[212:213], v[82:83], v[82:83]
	v_pk_mul_f32 v[216:217], v[84:85], v[84:85]
	v_pk_mul_f32 v[220:221], v[86:87], v[86:87]
	v_pk_mul_f32 v[224:225], v[88:89], v[88:89]
	v_add_f32_e32 v194, v196, v197
	v_add_f32_e32 v198, v200, v201
	v_add_f32_e32 v202, v204, v205
	v_add_f32_e32 v206, v208, v209
	v_add_f32_e32 v210, v212, v213
	v_add_f32_e32 v214, v216, v217
	v_add_f32_e32 v218, v220, v221
	v_add_f32_e32 v222, v224, v225
	v_add_f32_dpp v194, v194, v194 quad_perm:[1,0,3,2] row_mask:0xf bank_mask:0xf bound_ctrl:1
	v_add_f32_dpp v198, v198, v198 quad_perm:[1,0,3,2] row_mask:0xf bank_mask:0xf bound_ctrl:1
	v_add_f32_dpp v202, v202, v202 quad_perm:[1,0,3,2] row_mask:0xf bank_mask:0xf bound_ctrl:1
	v_add_f32_dpp v206, v206, v206 quad_perm:[1,0,3,2] row_mask:0xf bank_mask:0xf bound_ctrl:1
	v_add_f32_dpp v210, v210, v210 quad_perm:[1,0,3,2] row_mask:0xf bank_mask:0xf bound_ctrl:1
	v_add_f32_dpp v214, v214, v214 quad_perm:[1,0,3,2] row_mask:0xf bank_mask:0xf bound_ctrl:1
	v_add_f32_dpp v218, v218, v218 quad_perm:[1,0,3,2] row_mask:0xf bank_mask:0xf bound_ctrl:1
	v_add_f32_dpp v222, v222, v222 quad_perm:[1,0,3,2] row_mask:0xf bank_mask:0xf bound_ctrl:1
	v_add_f32_dpp v194, v194, v194 quad_perm:[2,3,0,1] row_mask:0xf bank_mask:0xf bound_ctrl:1
	v_add_f32_dpp v198, v198, v198 quad_perm:[2,3,0,1] row_mask:0xf bank_mask:0xf bound_ctrl:1
	v_add_f32_dpp v202, v202, v202 quad_perm:[2,3,0,1] row_mask:0xf bank_mask:0xf bound_ctrl:1
	v_add_f32_dpp v206, v206, v206 quad_perm:[2,3,0,1] row_mask:0xf bank_mask:0xf bound_ctrl:1
	v_add_f32_dpp v210, v210, v210 quad_perm:[2,3,0,1] row_mask:0xf bank_mask:0xf bound_ctrl:1
	v_add_f32_dpp v214, v214, v214 quad_perm:[2,3,0,1] row_mask:0xf bank_mask:0xf bound_ctrl:1
	v_add_f32_dpp v218, v218, v218 quad_perm:[2,3,0,1] row_mask:0xf bank_mask:0xf bound_ctrl:1
	v_add_f32_dpp v222, v222, v222 quad_perm:[2,3,0,1] row_mask:0xf bank_mask:0xf bound_ctrl:1
	v_add_f32_dpp v194, v194, v194 row_half_mirror row_mask:0xf bank_mask:0xf bound_ctrl:1
	v_add_f32_dpp v198, v198, v198 row_half_mirror row_mask:0xf bank_mask:0xf bound_ctrl:1
	v_add_f32_dpp v202, v202, v202 row_half_mirror row_mask:0xf bank_mask:0xf bound_ctrl:1
	v_add_f32_dpp v206, v206, v206 row_half_mirror row_mask:0xf bank_mask:0xf bound_ctrl:1
	v_add_f32_dpp v210, v210, v210 row_half_mirror row_mask:0xf bank_mask:0xf bound_ctrl:1
	v_add_f32_dpp v214, v214, v214 row_half_mirror row_mask:0xf bank_mask:0xf bound_ctrl:1
	v_add_f32_dpp v218, v218, v218 row_half_mirror row_mask:0xf bank_mask:0xf bound_ctrl:1
	v_add_f32_dpp v222, v222, v222 row_half_mirror row_mask:0xf bank_mask:0xf bound_ctrl:1
	v_add_f32_dpp v194, v194, v194 row_mirror row_mask:0xf bank_mask:0xf bound_ctrl:1
	v_add_f32_dpp v198, v198, v198 row_mirror row_mask:0xf bank_mask:0xf bound_ctrl:1
	v_add_f32_dpp v202, v202, v202 row_mirror row_mask:0xf bank_mask:0xf bound_ctrl:1
	v_add_f32_dpp v206, v206, v206 row_mirror row_mask:0xf bank_mask:0xf bound_ctrl:1
	v_add_f32_dpp v210, v210, v210 row_mirror row_mask:0xf bank_mask:0xf bound_ctrl:1
	v_add_f32_dpp v214, v214, v214 row_mirror row_mask:0xf bank_mask:0xf bound_ctrl:1
	v_add_f32_dpp v218, v218, v218 row_mirror row_mask:0xf bank_mask:0xf bound_ctrl:1
	v_add_f32_dpp v222, v222, v222 row_mirror row_mask:0xf bank_mask:0xf bound_ctrl:1
	ds_bpermute_b32 v195, v239, v194
	ds_bpermute_b32 v199, v239, v198
	ds_bpermute_b32 v203, v239, v202
	ds_bpermute_b32 v207, v239, v206
	ds_bpermute_b32 v211, v239, v210
	ds_bpermute_b32 v215, v239, v214
	ds_bpermute_b32 v219, v239, v218
	ds_bpermute_b32 v223, v239, v222
	s_waitcnt lgkmcnt(7)
	v_add_f32_e32 v194, v194, v195
	s_waitcnt lgkmcnt(6)
	v_add_f32_e32 v198, v198, v199
	s_waitcnt lgkmcnt(5)
	v_add_f32_e32 v202, v202, v203
	s_waitcnt lgkmcnt(4)
	v_add_f32_e32 v206, v206, v207
	s_waitcnt lgkmcnt(3)
	v_add_f32_e32 v210, v210, v211
	s_waitcnt lgkmcnt(2)
	v_add_f32_e32 v214, v214, v215
	s_waitcnt lgkmcnt(1)
	v_add_f32_e32 v218, v218, v219
	s_waitcnt lgkmcnt(0)
; __device__ __forceinline__ unsigned pk2(float lo, float hi) { f32x2v v = {lo, hi}; b16x2v b = __builtin_convertvector(v, b16x2v); return __builtin_bit_cast(unsigned, b); }
; __device__ __forceinline__ float fsigmoid(float x) { return __builtin_amdgcn_rcpf(1.0f + __expf(-x)); }
; __device__ __forceinline__ f32x2v bf2(unsigned v) { return (f32x2v){bflo(v), bfhi(v)}; }
; __device__ __forceinline__ void gn_swish_store(float v0, float v1, f32x2v gg, f32x2v gb, unsigned* dst) {
;     ...
;     const float rstd = rsqrtf(half_wave_sum(d0 * d0 + d1 * d1) * (1.0f / 64.0f) + LN_EPS);
;     float y0 = d0 * rstd * gg.x + gb.x, y1 = d1 * rstd * gg.y + gb.y;
;     y0 = y0 * fsigmoid(y0); y1 = y1 * fsigmoid(y1);
;     *dst = pk2(y0, y1);
; __device__ __forceinline__ void mixer_prompt_run(const Args& p, int run, int c2) {
;     ...
;                 const int ti = t0 + 8 * hh - 30 + i; unsigned v = U32[(rowb + (ti >= 0 ? ti : 0)) * 256 + c2]; v = (ti >= 0) ? v : 0u; const f32x2v x = bf2(v);
	v_add_f32_e32 v222, v222, v223
	v_fma_f32 v194, v194, s48, v241
	v_fma_f32 v198, v198, s48, v241
	v_fma_f32 v202, v202, s48, v241
	v_fma_f32 v206, v206, s48, v241
	v_fma_f32 v210, v210, s48, v241
	v_fma_f32 v214, v214, s48, v241
	v_fma_f32 v218, v218, s48, v241
	v_fma_f32 v222, v222, s48, v241
	v_rsq_f32_e32 v194, v194
	v_rsq_f32_e32 v198, v198
	v_rsq_f32_e32 v202, v202
	v_rsq_f32_e32 v206, v206
	v_rsq_f32_e32 v210, v210
	v_rsq_f32_e32 v214, v214
	v_rsq_f32_e32 v218, v218
	v_rsq_f32_e32 v222, v222
	v_pk_mul_f32 v[188:189], v[188:189], v[194:195] op_sel_hi:[1,0]
	v_pk_mul_f32 v[190:191], v[190:191], v[198:199] op_sel_hi:[1,0]
	v_pk_mul_f32 v[78:79], v[78:79], v[202:203] op_sel_hi:[1,0]
	v_pk_mul_f32 v[80:81], v[80:81], v[206:207] op_sel_hi:[1,0]
	v_pk_mul_f32 v[82:83], v[82:83], v[210:211] op_sel_hi:[1,0]
	v_pk_mul_f32 v[84:85], v[84:85], v[214:215] op_sel_hi:[1,0]
	v_pk_mul_f32 v[86:87], v[86:87], v[218:219] op_sel_hi:[1,0]
	v_pk_mul_f32 v[88:89], v[88:89], v[222:223] op_sel_hi:[1,0]
	v_pk_fma_f32 v[188:189], v[188:189], v[92:93], v[94:95]
	v_pk_fma_f32 v[190:191], v[190:191], v[92:93], v[94:95]
	v_pk_fma_f32 v[78:79], v[78:79], v[92:93], v[94:95]
	v_pk_fma_f32 v[80:81], v[80:81], v[92:93], v[94:95]
	v_pk_fma_f32 v[82:83], v[82:83], v[92:93], v[94:95]
	v_pk_fma_f32 v[84:85], v[84:85], v[92:93], v[94:95]
	v_pk_fma_f32 v[86:87], v[86:87], v[92:93], v[94:95]
	v_pk_fma_f32 v[88:89], v[88:89], v[92:93], v[94:95]
	v_pk_mul_f32 v[196:197], v[188:189], s[80:81]
	v_pk_mul_f32 v[200:201], v[190:191], s[80:81]
	v_pk_mul_f32 v[204:205], v[78:79], s[80:81]
	v_pk_mul_f32 v[208:209], v[80:81], s[80:81]
	v_pk_mul_f32 v[212:213], v[82:83], s[80:81]
	v_pk_mul_f32 v[216:217], v[84:85], s[80:81]
	v_pk_mul_f32 v[220:221], v[86:87], s[80:81]
	v_pk_mul_f32 v[224:225], v[88:89], s[80:81]
	v_exp_f32_e32 v196, v196
	v_exp_f32_e32 v197, v197
	v_exp_f32_e32 v200, v200
	v_exp_f32_e32 v201, v201
	v_exp_f32_e32 v204, v204
	v_exp_f32_e32 v205, v205
	v_exp_f32_e32 v208, v208
	v_exp_f32_e32 v209, v209
	v_exp_f32_e32 v212, v212
	v_exp_f32_e32 v213, v213
	v_exp_f32_e32 v216, v216
	v_exp_f32_e32 v217, v217
	v_exp_f32_e32 v220, v220
	v_exp_f32_e32 v221, v221
	v_exp_f32_e32 v224, v224
	v_exp_f32_e32 v225, v225
	v_pk_add_f32 v[196:197], v[196:197], s[86:87]
	v_pk_add_f32 v[200:201], v[200:201], s[86:87]
	v_pk_add_f32 v[204:205], v[204:205], s[86:87]
	v_pk_add_f32 v[208:209], v[208:209], s[86:87]
	v_pk_add_f32 v[212:213], v[212:213], s[86:87]
	v_pk_add_f32 v[216:217], v[216:217], s[86:87]
	v_pk_add_f32 v[220:221], v[220:221], s[86:87]
	v_pk_add_f32 v[224:225], v[224:225], s[86:87]
	v_rcp_f32_e32 v196, v196
	v_rcp_f32_e32 v197, v197
	v_rcp_f32_e32 v200, v200
	v_rcp_f32_e32 v201, v201
	v_rcp_f32_e32 v204, v204
	v_rcp_f32_e32 v205, v205
	v_rcp_f32_e32 v208, v208
	v_rcp_f32_e32 v209, v209
	v_rcp_f32_e32 v212, v212
	v_rcp_f32_e32 v213, v213
	v_rcp_f32_e32 v216, v216
	v_rcp_f32_e32 v217, v217
	v_rcp_f32_e32 v220, v220
	v_rcp_f32_e32 v221, v221
	v_rcp_f32_e32 v224, v224
	v_rcp_f32_e32 v225, v225
	v_pk_mul_f32 v[188:189], v[188:189], v[196:197]
	v_pk_mul_f32 v[190:191], v[190:191], v[200:201]
	v_pk_mul_f32 v[78:79], v[78:79], v[204:205]
	v_pk_mul_f32 v[80:81], v[80:81], v[208:209]
	v_pk_mul_f32 v[82:83], v[82:83], v[212:213]
	v_pk_mul_f32 v[84:85], v[84:85], v[216:217]
	v_pk_mul_f32 v[86:87], v[86:87], v[220:221]
	v_pk_mul_f32 v[88:89], v[88:89], v[224:225]
	v_cvt_pk_bf16_f32 v194, v188, v189
	v_cvt_pk_bf16_f32 v198, v190, v191
	v_cvt_pk_bf16_f32 v202, v78, v79
	v_cvt_pk_bf16_f32 v206, v80, v81
	v_cvt_pk_bf16_f32 v210, v82, v83
	v_cvt_pk_bf16_f32 v214, v84, v85
	v_cvt_pk_bf16_f32 v218, v86, v87
	v_cvt_pk_bf16_f32 v222, v88, v89
	s_add_u32 s70, s70, 0x2000
	s_addc_u32 s71, s71, 0
	global_store_dword v105, v194, s[70:71] offset:-4096
	global_store_dword v105, v198, s[70:71] offset:-2048
	global_store_dword v105, v202, s[70:71] offset:0
	global_store_dword v105, v206, s[70:71] offset:2048
	s_add_u32 s70, s70, 0x2000
	s_addc_u32 s71, s71, 0
	global_store_dword v105, v210, s[70:71] offset:-4096
	global_store_dword v105, v214, s[70:71] offset:-2048
	global_store_dword v105, v218, s[70:71] offset:0
	global_store_dword v105, v222, s[70:71] offset:2048
	s_branch .Lmx_done
.Lmx_edge:
	s_cmp_eq_u32 s64, 0
	s_cbranch_scc1 .Lmx_edge0
	v_mov_b32_e32 v172, v90
	v_mov_b32_e32 v173, v91
	v_mov_b32_e32 v174, v90
	v_mov_b32_e32 v175, v91
	v_mov_b32_e32 v176, v90
	v_mov_b32_e32 v177, v91
	v_mov_b32_e32 v178, v90
	v_mov_b32_e32 v179, v91
	v_mov_b32_e32 v180, v90
	v_mov_b32_e32 v181, v91
	v_mov_b32_e32 v182, v90
	v_mov_b32_e32 v183, v91
	v_mov_b32_e32 v184, v90
	v_mov_b32_e32 v185, v91
	v_mov_b32_e32 v186, v90
	v_mov_b32_e32 v187, v91
	v_mov_b32_e32 v188, v90
	v_mov_b32_e32 v189, v91
	v_mov_b32_e32 v190, v90
	v_mov_b32_e32 v191, v91
	v_mov_b32_e32 v78, v90
	v_mov_b32_e32 v79, v91
	v_mov_b32_e32 v80, v90
	v_mov_b32_e32 v81, v91
	v_mov_b32_e32 v82, v90
	v_mov_b32_e32 v83, v91
	v_mov_b32_e32 v84, v90
	v_mov_b32_e32 v85, v91
	s_branch .Lmx_row14
.Lmx_edge0:
	v_mov_b32_e32 v172, v90
	v_mov_b32_e32 v173, v91
	v_mov_b32_e32 v174, v90
	v_mov_b32_e32 v175, v91
	v_mov_b32_e32 v176, v90
	v_mov_b32_e32 v177, v91
	v_mov_b32_e32 v178, v90
	v_mov_b32_e32 v179, v91
	v_mov_b32_e32 v180, v90
	v_mov_b32_e32 v181, v91
	v_mov_b32_e32 v182, v90
	v_mov_b32_e32 v183, v91
	v_mov_b32_e32 v184, v90
	v_mov_b32_e32 v185, v91
	v_mov_b32_e32 v186, v90
	v_mov_b32_e32 v187, v91
	v_mov_b32_e32 v188, v90
	v_mov_b32_e32 v189, v91
	v_mov_b32_e32 v190, v90
	v_mov_b32_e32 v191, v91
	v_mov_b32_e32 v78, v90
	v_mov_b32_e32 v79, v91
	v_mov_b32_e32 v80, v90
	v_mov_b32_e32 v81, v91
	v_mov_b32_e32 v82, v90
	v_mov_b32_e32 v83, v91
	v_mov_b32_e32 v84, v90
	v_mov_b32_e32 v85, v91
	v_mov_b32_e32 v86, v90
	v_mov_b32_e32 v87, v91
	v_mov_b32_e32 v88, v90
	v_mov_b32_e32 v89, v91
	s_branch .Lmx_row30
